# top-k extraction: sorted lists in aligned register pairs, pops as exec-masked v_pk_mov_b32 funnel moves, round result kept by exec-masked 64-bit moves (fewer VALU ops, same values)
# speedup vs baseline: 1.0154x; 1.0048x over previous
.LBB0_1346:
	s_mov_b32 s78, 0x10001
	s_mov_b32 s79, 0x10001
	v_mov_b32_e32 v70, 0
	v_mov_b32_e32 v71, 0
	v_add_co_u32_e32 v2, vcc, 0xe000, v0
	s_mov_b32 s40, 0
	s_nop 0
	v_addc_co_u32_e32 v3, vcc, 0, v1, vcc
	v_add_co_u32_e32 v4, vcc, 0xc000, v0
	s_mov_b64 s[0:1], vcc
	v_add_co_u32_e32 v6, vcc, 0xa000, v0
	s_nop 1
	v_addc_co_u32_e32 v7, vcc, 0, v1, vcc
	v_add_co_u32_e32 v8, vcc, 0x8000, v0
	s_nop 1
	v_addc_co_u32_e32 v9, vcc, 0, v1, vcc
	v_add_co_u32_e32 v10, vcc, 0x6000, v0
	s_nop 1
	v_addc_co_u32_e32 v11, vcc, 0, v1, vcc
	v_add_co_u32_e32 v14, vcc, 0x4000, v0
	s_nop 1
	v_addc_co_u32_e32 v15, vcc, 0, v1, vcc
	v_add_co_u32_e32 v18, vcc, 0x2000, v0
	s_nop 1
	v_addc_co_u32_e32 v19, vcc, 0, v1, vcc
	global_load_dwordx4 v[18:21], v[18:19], off
	s_nop 0
	global_load_dwordx4 v[22:25], v[0:1], off
	global_load_dwordx4 v[26:29], v[10:11], off
	global_load_dwordx4 v[30:33], v[14:15], off
	global_load_dwordx4 v[34:37], v[6:7], off
	global_load_dwordx4 v[38:41], v[8:9], off
	v_addc_co_u32_e64 v5, vcc, 0, v1, s[0:1]
	global_load_dwordx4 v[42:45], v[4:5], off
	global_load_dwordx4 v[46:49], v[2:3], off
	global_load_dwordx4 v[50:53], v[12:13], off
	global_load_dwordx4 v[54:57], v[12:13], off offset:64
	global_load_dwordx4 v[58:61], v[12:13], off offset:128
	global_load_dwordx4 v[62:65], v[12:13], off offset:192
	s_nop 0
	global_load_dwordx4 v[0:3], v[12:13], off offset:448
	global_load_dwordx4 v[4:7], v[12:13], off offset:384
	global_load_dwordx4 v[8:11], v[12:13], off offset:320
	s_nop 0
	global_load_dwordx4 v[12:15], v[12:13], off offset:256
	s_waitcnt lgkmcnt(0)
	s_barrier
	s_waitcnt vmcnt(14)
	ds_write_b128 v208, v[22:25]
	ds_write_b128 v209, v[18:21]
	s_waitcnt vmcnt(12)
	ds_write_b128 v210, v[30:33]
	ds_write_b128 v211, v[26:29]
	s_waitcnt vmcnt(10)
	ds_write_b128 v212, v[38:41]
	ds_write_b128 v213, v[34:37]
	s_waitcnt vmcnt(9)
	ds_write_b128 v214, v[42:45]
	s_waitcnt vmcnt(8)
	ds_write_b128 v215, v[46:49]
	s_waitcnt lgkmcnt(0)
	s_barrier
	ds_read_b128 v[18:21], v184
	ds_read_b128 v[22:25], v184 offset:64
	s_waitcnt vmcnt(7) lgkmcnt(1)
	v_mfma_f32_16x16x32_bf16 v[18:21], v[50:53], v[18:21], 0
	s_waitcnt vmcnt(6) lgkmcnt(0)
	v_mfma_f32_16x16x32_bf16 v[18:21], v[54:57], v[22:25], v[18:21]
	ds_read_b128 v[22:25], v184 offset:128
	ds_read_b128 v[26:29], v184 offset:192
	s_waitcnt vmcnt(5) lgkmcnt(1)
	v_mfma_f32_16x16x32_bf16 v[18:21], v[58:61], v[22:25], v[18:21]
	s_waitcnt vmcnt(4) lgkmcnt(0)
	v_mfma_f32_16x16x32_bf16 v[18:21], v[62:65], v[26:29], v[18:21]
	ds_read_b128 v[22:25], v184 offset:4352
	ds_read_b128 v[26:29], v184 offset:4416
	s_waitcnt lgkmcnt(1)
	v_mfma_f32_16x16x32_bf16 v[22:25], v[50:53], v[22:25], 0
	s_waitcnt lgkmcnt(0)
	v_mfma_f32_16x16x32_bf16 v[22:25], v[54:57], v[26:29], v[22:25]
	ds_read_b128 v[26:29], v184 offset:4480
	ds_read_b128 v[30:33], v184 offset:4544
	s_waitcnt lgkmcnt(1)
	v_mfma_f32_16x16x32_bf16 v[22:25], v[58:61], v[26:29], v[22:25]
	s_waitcnt lgkmcnt(0)
	v_mfma_f32_16x16x32_bf16 v[22:25], v[62:65], v[30:33], v[22:25]
	ds_read_b128 v[26:29], v184 offset:8704
	ds_read_b128 v[30:33], v184 offset:8768
	s_waitcnt lgkmcnt(1)
	v_mfma_f32_16x16x32_bf16 v[26:29], v[50:53], v[26:29], 0
	s_waitcnt lgkmcnt(0)
	v_mfma_f32_16x16x32_bf16 v[26:29], v[54:57], v[30:33], v[26:29]
	ds_read_b128 v[30:33], v184 offset:8832
	ds_read_b128 v[34:37], v184 offset:8896
	s_waitcnt lgkmcnt(1)
	v_mfma_f32_16x16x32_bf16 v[26:29], v[58:61], v[30:33], v[26:29]
	s_waitcnt lgkmcnt(0)
	v_mfma_f32_16x16x32_bf16 v[26:29], v[62:65], v[34:37], v[26:29]
	ds_read_b128 v[30:33], v184 offset:13056
	ds_read_b128 v[34:37], v184 offset:13120
	s_waitcnt lgkmcnt(1)
	v_mfma_f32_16x16x32_bf16 v[30:33], v[50:53], v[30:33], 0
	s_waitcnt lgkmcnt(0)
	v_mfma_f32_16x16x32_bf16 v[30:33], v[54:57], v[34:37], v[30:33]
	ds_read_b128 v[34:37], v184 offset:13184
	ds_read_b128 v[38:41], v184 offset:13248
	s_waitcnt lgkmcnt(1)
	v_mfma_f32_16x16x32_bf16 v[30:33], v[58:61], v[34:37], v[30:33]
	s_waitcnt lgkmcnt(0)
	v_mfma_f32_16x16x32_bf16 v[30:33], v[62:65], v[38:41], v[30:33]
	ds_read_b128 v[34:37], v184 offset:17408
	ds_read_b128 v[38:41], v184 offset:17472
	s_waitcnt lgkmcnt(1)
	v_mfma_f32_16x16x32_bf16 v[34:37], v[50:53], v[34:37], 0
	s_waitcnt lgkmcnt(0)
	v_mfma_f32_16x16x32_bf16 v[34:37], v[54:57], v[38:41], v[34:37]
	ds_read_b128 v[38:41], v184 offset:17536
	ds_read_b128 v[42:45], v184 offset:17600
	s_waitcnt lgkmcnt(1)
	v_mfma_f32_16x16x32_bf16 v[34:37], v[58:61], v[38:41], v[34:37]
	s_waitcnt lgkmcnt(0)
	v_mfma_f32_16x16x32_bf16 v[34:37], v[62:65], v[42:45], v[34:37]
	ds_read_b128 v[38:41], v184 offset:21760
	ds_read_b128 v[42:45], v184 offset:21824
	s_waitcnt lgkmcnt(1)
	v_mfma_f32_16x16x32_bf16 v[38:41], v[50:53], v[38:41], 0
	s_waitcnt lgkmcnt(0)
	v_mfma_f32_16x16x32_bf16 v[38:41], v[54:57], v[42:45], v[38:41]
	ds_read_b128 v[42:45], v184 offset:21888
	ds_read_b128 v[46:49], v184 offset:21952
	s_waitcnt lgkmcnt(1)
	v_mfma_f32_16x16x32_bf16 v[38:41], v[58:61], v[42:45], v[38:41]
	s_waitcnt lgkmcnt(0)
	v_mfma_f32_16x16x32_bf16 v[38:41], v[62:65], v[46:49], v[38:41]
	ds_read_b128 v[42:45], v184 offset:26112
	ds_read_b128 v[46:49], v184 offset:26176
	s_waitcnt lgkmcnt(1)
	v_mfma_f32_16x16x32_bf16 v[42:45], v[50:53], v[42:45], 0
	s_waitcnt lgkmcnt(0)
	v_mfma_f32_16x16x32_bf16 v[42:45], v[54:57], v[46:49], v[42:45]
	ds_read_b128 v[46:49], v184 offset:26240
	ds_read_b128 v[66:69], v184 offset:26304
	s_waitcnt lgkmcnt(1)
	v_mfma_f32_16x16x32_bf16 v[42:45], v[58:61], v[46:49], v[42:45]
	s_waitcnt lgkmcnt(0)
	v_mfma_f32_16x16x32_bf16 v[42:45], v[62:65], v[66:69], v[42:45]
	ds_read_b128 v[46:49], v184 offset:30464
	ds_read_b128 v[66:69], v184 offset:30528
	s_waitcnt lgkmcnt(1)
	v_mfma_f32_16x16x32_bf16 v[46:49], v[50:53], v[46:49], 0
	s_waitcnt lgkmcnt(0)
	v_mfma_f32_16x16x32_bf16 v[46:49], v[54:57], v[66:69], v[46:49]
	ds_read_b128 v[50:53], v184 offset:30592
	ds_read_b128 v[54:57], v184 offset:30656
	s_waitcnt lgkmcnt(1)
	v_mfma_f32_16x16x32_bf16 v[46:49], v[58:61], v[50:53], v[46:49]
	s_waitcnt lgkmcnt(0)
	v_mfma_f32_16x16x32_bf16 v[46:49], v[62:65], v[54:57], v[46:49]
	s_nop 7
	s_nop 1
	v_ashrrev_i32_e32 v50, 31, v49
	v_bitop3_b32 v49, v49, v50, v217 bitop3:0x1e
	v_and_or_b32 v49, v49, s67, v178
	v_ashrrev_i32_e32 v50, 31, v45
	v_bitop3_b32 v45, v45, v50, v217 bitop3:0x1e
	v_and_or_b32 v50, v45, s67, v177
	v_ashrrev_i32_e32 v45, 31, v41
	v_bitop3_b32 v41, v41, v45, v217 bitop3:0x1e
	v_and_or_b32 v51, v41, s67, v176
	v_ashrrev_i32_e32 v41, 31, v37
	v_bitop3_b32 v37, v37, v41, v217 bitop3:0x1e
	v_and_or_b32 v52, v37, s67, v175
	v_ashrrev_i32_e32 v37, 31, v33
	v_bitop3_b32 v33, v33, v37, v217 bitop3:0x1e
	v_and_or_b32 v53, v33, s67, v170
	v_ashrrev_i32_e32 v33, 31, v29
	v_bitop3_b32 v29, v29, v33, v217 bitop3:0x1e
	v_and_or_b32 v54, v29, s67, v181
	v_ashrrev_i32_e32 v29, 31, v25
	v_bitop3_b32 v25, v25, v29, v217 bitop3:0x1e
	v_and_or_b32 v55, v25, s67, v180
	v_ashrrev_i32_e32 v25, 31, v21
	v_bitop3_b32 v21, v21, v25, v217 bitop3:0x1e
	v_and_or_b32 v21, v21, s67, v179
	v_ashrrev_i32_e32 v25, 31, v48
	v_bitop3_b32 v25, v48, v25, v217 bitop3:0x1e
	v_and_or_b32 v41, v25, s67, v178
	v_ashrrev_i32_e32 v25, 31, v44
	v_bitop3_b32 v25, v44, v25, v217 bitop3:0x1e
	v_and_or_b32 v44, v25, s67, v177
	v_ashrrev_i32_e32 v25, 31, v40
	v_bitop3_b32 v25, v40, v25, v217 bitop3:0x1e
	v_and_or_b32 v40, v25, s67, v176
	v_ashrrev_i32_e32 v25, 31, v36
	v_bitop3_b32 v25, v36, v25, v217 bitop3:0x1e
	v_and_or_b32 v45, v25, s67, v175
	v_ashrrev_i32_e32 v25, 31, v32
	v_bitop3_b32 v25, v32, v25, v217 bitop3:0x1e
	v_and_or_b32 v48, v25, s67, v170
	v_ashrrev_i32_e32 v25, 31, v28
	v_bitop3_b32 v25, v28, v25, v217 bitop3:0x1e
	v_and_or_b32 v56, v25, s67, v181
	v_ashrrev_i32_e32 v25, 31, v24
	v_bitop3_b32 v24, v24, v25, v217 bitop3:0x1e
	v_and_or_b32 v57, v24, s67, v180
	v_ashrrev_i32_e32 v24, 31, v20
	v_bitop3_b32 v20, v20, v24, v217 bitop3:0x1e
	v_and_or_b32 v20, v20, s67, v179
	v_ashrrev_i32_e32 v24, 31, v47
	v_bitop3_b32 v24, v47, v24, v217 bitop3:0x1e
	v_and_or_b32 v32, v24, s67, v178
	v_min_u32_e32 v47, v52, v51
	v_ashrrev_i32_e32 v24, 31, v43
	v_bitop3_b32 v24, v43, v24, v217 bitop3:0x1e
	v_and_or_b32 v33, v24, s67, v177
	v_ashrrev_i32_e32 v24, 31, v39
	v_bitop3_b32 v24, v39, v24, v217 bitop3:0x1e
	v_and_or_b32 v36, v24, s67, v176
	v_ashrrev_i32_e32 v24, 31, v35
	v_bitop3_b32 v24, v35, v24, v217 bitop3:0x1e
	v_and_or_b32 v35, v24, s67, v175
	v_ashrrev_i32_e32 v24, 31, v31
	v_bitop3_b32 v24, v31, v24, v217 bitop3:0x1e
	v_and_or_b32 v31, v24, s67, v170
	v_ashrrev_i32_e32 v24, 31, v27
	v_bitop3_b32 v24, v27, v24, v217 bitop3:0x1e
	v_and_or_b32 v37, v24, s67, v181
	v_ashrrev_i32_e32 v24, 31, v23
	v_bitop3_b32 v23, v23, v24, v217 bitop3:0x1e
	v_and_or_b32 v39, v23, s67, v180
	v_ashrrev_i32_e32 v23, 31, v19
	v_bitop3_b32 v19, v19, v23, v217 bitop3:0x1e
	v_and_or_b32 v19, v19, s67, v179
	v_ashrrev_i32_e32 v23, 31, v46
	v_bitop3_b32 v23, v46, v23, v217 bitop3:0x1e
	v_and_or_b32 v23, v23, s67, v178
	v_ashrrev_i32_e32 v24, 31, v42
	v_bitop3_b32 v24, v42, v24, v217 bitop3:0x1e
	v_and_or_b32 v24, v24, s67, v177
	v_ashrrev_i32_e32 v25, 31, v38
	v_bitop3_b32 v25, v38, v25, v217 bitop3:0x1e
	v_and_or_b32 v25, v25, s67, v176
	v_ashrrev_i32_e32 v27, 31, v34
	v_bitop3_b32 v27, v34, v27, v217 bitop3:0x1e
	v_and_or_b32 v27, v27, s67, v175
	v_ashrrev_i32_e32 v28, 31, v30
	v_bitop3_b32 v28, v30, v28, v217 bitop3:0x1e
	v_and_or_b32 v28, v28, s67, v170
	v_ashrrev_i32_e32 v29, 31, v26
	v_bitop3_b32 v26, v26, v29, v217 bitop3:0x1e
	v_and_or_b32 v26, v26, s67, v181
	v_ashrrev_i32_e32 v29, 31, v22
	v_bitop3_b32 v22, v22, v29, v217 bitop3:0x1e
	v_and_or_b32 v22, v22, s67, v180
	v_ashrrev_i32_e32 v29, 31, v18
	v_bitop3_b32 v18, v18, v29, v217 bitop3:0x1e
	v_and_or_b32 v18, v18, s67, v179
	v_max_u32_e32 v29, v18, v22
	v_min_u32_e32 v18, v18, v22
	v_max_u32_e32 v22, v26, v28
	v_min_u32_e32 v26, v26, v28
	v_max_u32_e32 v28, v27, v25
	v_min_u32_e32 v25, v27, v25
	v_max_u32_e32 v27, v24, v23
	v_min_u32_e32 v23, v24, v23
	v_max_u32_e32 v24, v29, v22
	v_min_u32_e32 v22, v29, v22
	v_max_u32_e32 v29, v18, v26
	v_min_u32_e32 v18, v18, v26
	v_max_u32_e32 v26, v28, v27
	v_min_u32_e32 v27, v28, v27
	v_max_u32_e32 v28, v25, v23
	v_min_u32_e32 v23, v25, v23
	v_max_u32_e32 v25, v29, v22
	v_min_u32_e32 v29, v29, v22
	v_max_u32_e32 v30, v28, v27
	v_min_u32_e32 v27, v28, v27
	v_max_u32_e32 v22, v24, v26
	v_min_u32_e32 v24, v24, v26
	v_max_u32_e32 v26, v25, v30
	v_min_u32_e32 v25, v25, v30
	v_max_u32_e32 v28, v29, v27
	v_min_u32_e32 v29, v29, v27
	v_max_u32_e32 v27, v18, v23
	v_min_u32_e32 v23, v18, v23
	v_max_u32_e32 v18, v28, v24
	v_min_u32_e32 v28, v28, v24
	v_max_u32_e32 v30, v27, v25
	v_min_u32_e32 v34, v27, v25
	v_max_u32_e32 v24, v26, v18
	v_min_u32_e32 v25, v26, v18
	v_max_u32_e32 v26, v30, v28
	v_min_u32_e32 v27, v30, v28
	v_max_u32_e32 v28, v34, v29
	v_min_u32_e32 v29, v34, v29
	v_max_u32_e32 v18, v19, v39
	v_min_u32_e32 v19, v19, v39
	v_max_u32_e32 v30, v37, v31
	v_min_u32_e32 v31, v37, v31
	v_max_u32_e32 v34, v35, v36
	v_min_u32_e32 v35, v35, v36
	v_max_u32_e32 v36, v33, v32
	v_min_u32_e32 v32, v33, v32
	v_max_u32_e32 v33, v18, v30
	v_min_u32_e32 v18, v18, v30
	v_max_u32_e32 v30, v19, v31
	v_min_u32_e32 v19, v19, v31
	v_max_u32_e32 v31, v34, v36
	v_min_u32_e32 v34, v34, v36
	v_max_u32_e32 v36, v35, v32
	v_min_u32_e32 v32, v35, v32
	v_max_u32_e32 v35, v30, v18
	v_min_u32_e32 v18, v30, v18
	v_max_u32_e32 v37, v36, v34
	v_min_u32_e32 v34, v36, v34
	v_max_u32_e32 v30, v33, v31
	v_min_u32_e32 v33, v33, v31
	v_max_u32_e32 v36, v35, v37
	v_min_u32_e32 v35, v35, v37
	v_max_u32_e32 v37, v18, v34
	v_min_u32_e32 v18, v18, v34
	v_max_u32_e32 v34, v19, v32
	v_min_u32_e32 v31, v19, v32
	v_max_u32_e32 v19, v37, v33
	v_min_u32_e32 v37, v37, v33
	v_max_u32_e32 v38, v34, v35
	v_min_u32_e32 v39, v34, v35
	v_max_u32_e32 v32, v36, v19
	v_min_u32_e32 v33, v36, v19
	v_max_u32_e32 v34, v38, v37
	v_min_u32_e32 v35, v38, v37
	v_max_u32_e32 v36, v39, v18
	v_min_u32_e32 v37, v39, v18
	v_max_u32_e32 v18, v20, v57
	v_min_u32_e32 v19, v20, v57
	v_max_u32_e32 v20, v56, v48
	v_min_u32_e32 v38, v56, v48
	v_max_u32_e32 v39, v45, v40
	v_min_u32_e32 v40, v45, v40
	v_max_u32_e32 v42, v44, v41
	v_min_u32_e32 v41, v44, v41
	v_max_u32_e32 v43, v18, v20
	v_min_u32_e32 v18, v18, v20
	v_max_u32_e32 v20, v19, v38
	v_min_u32_e32 v19, v19, v38
	v_max_u32_e32 v44, v39, v42
	v_min_u32_e32 v38, v39, v42
	v_max_u32_e32 v39, v40, v41
	v_min_u32_e32 v40, v40, v41
	v_max_u32_e32 v41, v20, v18
	v_min_u32_e32 v18, v20, v18
	v_max_u32_e32 v20, v39, v38
	v_min_u32_e32 v39, v39, v38
	v_max_u32_e32 v38, v43, v44
	v_min_u32_e32 v42, v43, v44
	v_max_u32_e32 v43, v41, v20
	v_min_u32_e32 v20, v41, v20
	v_max_u32_e32 v41, v18, v39
	v_max_u32_e32 v44, v19, v40
	v_min_u32_e32 v18, v18, v39
	v_min_u32_e32 v39, v19, v40
	v_max_u32_e32 v19, v41, v42
	v_min_u32_e32 v45, v41, v42
	v_max_u32_e32 v46, v44, v20
	v_min_u32_e32 v20, v44, v20
	v_max_u32_e32 v40, v43, v19
	v_min_u32_e32 v41, v43, v19
	v_max_u32_e32 v42, v46, v45
	v_min_u32_e32 v43, v46, v45
	v_max_u32_e32 v44, v20, v18
	v_min_u32_e32 v45, v20, v18
	v_max_u32_e32 v18, v21, v55
	v_min_u32_e32 v19, v21, v55
	v_max_u32_e32 v20, v54, v53
	v_min_u32_e32 v21, v54, v53
	v_max_u32_e32 v46, v52, v51
	v_max_u32_e32 v48, v50, v49
	v_min_u32_e32 v49, v50, v49
	v_max_u32_e32 v50, v18, v20
	v_min_u32_e32 v18, v18, v20
	v_max_u32_e32 v20, v19, v21
	v_min_u32_e32 v19, v19, v21
	v_max_u32_e32 v21, v46, v48
	v_min_u32_e32 v46, v46, v48
	v_max_u32_e32 v48, v47, v49
	v_min_u32_e32 v47, v47, v49
	v_max_u32_e32 v49, v20, v18
	v_min_u32_e32 v18, v20, v18
	v_max_u32_e32 v20, v48, v46
	v_min_u32_e32 v48, v48, v46
	v_max_u32_e32 v46, v50, v21
	v_min_u32_e32 v21, v50, v21
	v_max_u32_e32 v50, v49, v20
	v_min_u32_e32 v20, v49, v20
	v_max_u32_e32 v49, v18, v48
	v_min_u32_e32 v18, v18, v48
	v_max_u32_e32 v48, v19, v47
	v_min_u32_e32 v47, v19, v47
	v_max_u32_e32 v19, v49, v21
	v_min_u32_e32 v21, v49, v21
	v_max_u32_e32 v51, v48, v20
	v_min_u32_e32 v20, v48, v20
	v_max_u32_e32 v48, v50, v19
	v_min_u32_e32 v49, v50, v19
	v_max_u32_e32 v50, v51, v21
	v_min_u32_e32 v51, v51, v21
	v_max_u32_e32 v52, v20, v18
	v_min_u32_e32 v53, v20, v18
	v_mov_b32_e32 v18, 0
	v_mov_b32_e32 v19, 0
	v_mov_b32_e32 v20, 0
	v_mov_b32_e32 v21, 0
	v_pk_mov_b32 v[72:73], v[30:31], v[32:33] op_sel:[0,0] op_sel_hi:[0,0]
	v_pk_mov_b32 v[74:75], v[32:33], v[34:35] op_sel:[1,0] op_sel_hi:[1,0]
	v_pk_mov_b32 v[76:77], v[34:35], v[36:37] op_sel:[1,0] op_sel_hi:[1,0]
	v_pk_mov_b32 v[78:79], v[36:37], v[30:31] op_sel:[1,1] op_sel_hi:[1,1]
	v_pk_mov_b32 v[80:81], v[22:23], v[24:25] op_sel:[0,0] op_sel_hi:[0,0]
	v_pk_mov_b32 v[82:83], v[24:25], v[26:27] op_sel:[1,0] op_sel_hi:[1,0]
	v_pk_mov_b32 v[84:85], v[26:27], v[28:29] op_sel:[1,0] op_sel_hi:[1,0]
	v_pk_mov_b32 v[86:87], v[28:29], v[22:23] op_sel:[1,1] op_sel_hi:[1,1]
	v_pk_mov_b32 v[88:89], v[38:39], v[40:41] op_sel:[0,0] op_sel_hi:[0,0]
	v_pk_mov_b32 v[90:91], v[40:41], v[42:43] op_sel:[1,0] op_sel_hi:[1,0]
	v_pk_mov_b32 v[92:93], v[42:43], v[44:45] op_sel:[1,0] op_sel_hi:[1,0]
	v_pk_mov_b32 v[94:95], v[44:45], v[38:39] op_sel:[1,1] op_sel_hi:[1,1]
	v_pk_mov_b32 v[96:97], v[46:47], v[48:49] op_sel:[0,0] op_sel_hi:[0,0]
	v_pk_mov_b32 v[98:99], v[48:49], v[50:51] op_sel:[1,0] op_sel_hi:[1,0]
	v_pk_mov_b32 v[100:101], v[50:51], v[52:53] op_sel:[1,0] op_sel_hi:[1,0]
	v_pk_mov_b32 v[102:103], v[52:53], v[46:47] op_sel:[1,1] op_sel_hi:[1,1]
.LBB0_1347:
	v_max_u32_dpp v55, v72, v72 row_ror:1 row_mask:0xf bank_mask:0xf bound_ctrl:1
	v_max_u32_dpp v54, v80, v80 row_ror:1 row_mask:0xf bank_mask:0xf bound_ctrl:1
	v_max_u32_dpp v56, v88, v88 row_ror:1 row_mask:0xf bank_mask:0xf bound_ctrl:1
	v_max_u32_dpp v55, v55, v55 row_ror:2 row_mask:0xf bank_mask:0xf bound_ctrl:1
	v_max_u32_dpp v57, v96, v96 row_ror:1 row_mask:0xf bank_mask:0xf bound_ctrl:1
	v_max_u32_dpp v54, v54, v54 row_ror:2 row_mask:0xf bank_mask:0xf bound_ctrl:1
	v_max_u32_dpp v56, v56, v56 row_ror:2 row_mask:0xf bank_mask:0xf bound_ctrl:1
	v_max_u32_dpp v55, v55, v55 row_ror:4 row_mask:0xf bank_mask:0xf bound_ctrl:1
	v_max_u32_dpp v57, v57, v57 row_ror:2 row_mask:0xf bank_mask:0xf bound_ctrl:1
	v_max_u32_dpp v54, v54, v54 row_ror:4 row_mask:0xf bank_mask:0xf bound_ctrl:1
	v_max_u32_dpp v56, v56, v56 row_ror:4 row_mask:0xf bank_mask:0xf bound_ctrl:1
	v_max_u32_dpp v55, v55, v55 row_ror:8 row_mask:0xf bank_mask:0xf bound_ctrl:1
	v_max_u32_dpp v57, v57, v57 row_ror:4 row_mask:0xf bank_mask:0xf bound_ctrl:1
	v_max_u32_dpp v54, v54, v54 row_ror:8 row_mask:0xf bank_mask:0xf bound_ctrl:1
	v_max_u32_dpp v56, v56, v56 row_ror:8 row_mask:0xf bank_mask:0xf bound_ctrl:1
	v_max_u32_dpp v57, v57, v57 row_ror:8 row_mask:0xf bank_mask:0xf bound_ctrl:1
	v_cmp_eq_u32_e64 s[84:85], v72, v55
	v_cmp_eq_u32_e64 s[86:87], v80, v54
	v_cmp_eq_u32_e64 s[88:89], v88, v56
	v_cmp_eq_u32_e64 s[90:91], v96, v57
	s_mov_b64 exec, s[84:85]
	v_pk_mov_b32 v[72:73], v[72:73], v[74:75] op_sel:[1,0] op_sel_hi:[1,0]
	v_pk_mov_b32 v[74:75], v[74:75], v[76:77] op_sel:[1,0] op_sel_hi:[1,0]
	v_pk_mov_b32 v[76:77], v[76:77], v[78:79] op_sel:[1,0] op_sel_hi:[1,0]
	v_pk_mov_b32 v[78:79], v[78:79], v[70:71] op_sel:[1,0] op_sel_hi:[1,0]
	s_mov_b64 exec, s[86:87]
	v_pk_mov_b32 v[80:81], v[80:81], v[82:83] op_sel:[1,0] op_sel_hi:[1,0]
	v_pk_mov_b32 v[82:83], v[82:83], v[84:85] op_sel:[1,0] op_sel_hi:[1,0]
	v_pk_mov_b32 v[84:85], v[84:85], v[86:87] op_sel:[1,0] op_sel_hi:[1,0]
	v_pk_mov_b32 v[86:87], v[86:87], v[70:71] op_sel:[1,0] op_sel_hi:[1,0]
	s_mov_b64 exec, s[88:89]
	v_pk_mov_b32 v[88:89], v[88:89], v[90:91] op_sel:[1,0] op_sel_hi:[1,0]
	v_pk_mov_b32 v[90:91], v[90:91], v[92:93] op_sel:[1,0] op_sel_hi:[1,0]
	v_pk_mov_b32 v[92:93], v[92:93], v[94:95] op_sel:[1,0] op_sel_hi:[1,0]
	v_pk_mov_b32 v[94:95], v[94:95], v[70:71] op_sel:[1,0] op_sel_hi:[1,0]
	s_mov_b64 exec, s[90:91]
	v_pk_mov_b32 v[96:97], v[96:97], v[98:99] op_sel:[1,0] op_sel_hi:[1,0]
	v_pk_mov_b32 v[98:99], v[98:99], v[100:101] op_sel:[1,0] op_sel_hi:[1,0]
	v_pk_mov_b32 v[100:101], v[100:101], v[102:103] op_sel:[1,0] op_sel_hi:[1,0]
	v_pk_mov_b32 v[102:103], v[102:103], v[70:71] op_sel:[1,0] op_sel_hi:[1,0]
	s_lshl_b64 exec, s[78:79], s40
	s_add_i32 s40, s40, 1
	v_pk_mov_b32 v[18:19], v[54:55], v[54:55] op_sel:[0,1] op_sel_hi:[0,1]
	v_pk_mov_b32 v[20:21], v[56:57], v[56:57] op_sel:[0,1] op_sel_hi:[0,1]
	s_mov_b64 exec, -1
	s_cmp_lg_u32 s40, 8
	s_cbranch_scc1 .LBB0_1347
	v_max_u32_dpp v55, v72, v72 row_ror:1 row_mask:0xf bank_mask:0xf bound_ctrl:1
	v_max_u32_dpp v54, v80, v80 row_ror:1 row_mask:0xf bank_mask:0xf bound_ctrl:1
	v_max_u32_dpp v56, v88, v88 row_ror:1 row_mask:0xf bank_mask:0xf bound_ctrl:1
	v_max_u32_dpp v55, v55, v55 row_ror:2 row_mask:0xf bank_mask:0xf bound_ctrl:1
	v_max_u32_dpp v57, v96, v96 row_ror:1 row_mask:0xf bank_mask:0xf bound_ctrl:1
	v_max_u32_dpp v54, v54, v54 row_ror:2 row_mask:0xf bank_mask:0xf bound_ctrl:1
	v_max_u32_dpp v56, v56, v56 row_ror:2 row_mask:0xf bank_mask:0xf bound_ctrl:1
	v_max_u32_dpp v55, v55, v55 row_ror:4 row_mask:0xf bank_mask:0xf bound_ctrl:1
	v_max_u32_dpp v57, v57, v57 row_ror:2 row_mask:0xf bank_mask:0xf bound_ctrl:1
	v_max_u32_dpp v54, v54, v54 row_ror:4 row_mask:0xf bank_mask:0xf bound_ctrl:1
	v_max_u32_dpp v56, v56, v56 row_ror:4 row_mask:0xf bank_mask:0xf bound_ctrl:1
	v_max_u32_dpp v55, v55, v55 row_ror:8 row_mask:0xf bank_mask:0xf bound_ctrl:1
	v_max_u32_dpp v57, v57, v57 row_ror:4 row_mask:0xf bank_mask:0xf bound_ctrl:1
	v_max_u32_dpp v54, v54, v54 row_ror:8 row_mask:0xf bank_mask:0xf bound_ctrl:1
	v_max_u32_dpp v56, v56, v56 row_ror:8 row_mask:0xf bank_mask:0xf bound_ctrl:1
	v_max_u32_dpp v57, v57, v57 row_ror:8 row_mask:0xf bank_mask:0xf bound_ctrl:1
	v_cmp_eq_u32_e64 s[84:85], v72, v55
	v_cmp_eq_u32_e64 s[86:87], v80, v54
	v_cmp_eq_u32_e64 s[88:89], v88, v56
	v_cmp_eq_u32_e64 s[90:91], v96, v57
	s_mov_b64 exec, s[84:85]
	v_pk_mov_b32 v[72:73], v[72:73], v[74:75] op_sel:[1,0] op_sel_hi:[1,0]
	v_pk_mov_b32 v[74:75], v[74:75], v[76:77] op_sel:[1,0] op_sel_hi:[1,0]
	v_pk_mov_b32 v[76:77], v[76:77], v[78:79] op_sel:[1,0] op_sel_hi:[1,0]
	v_pk_mov_b32 v[78:79], v[78:79], v[70:71] op_sel:[1,0] op_sel_hi:[1,0]
	s_mov_b64 exec, s[86:87]
	v_pk_mov_b32 v[80:81], v[80:81], v[82:83] op_sel:[1,0] op_sel_hi:[1,0]
	v_pk_mov_b32 v[82:83], v[82:83], v[84:85] op_sel:[1,0] op_sel_hi:[1,0]
	v_pk_mov_b32 v[84:85], v[84:85], v[86:87] op_sel:[1,0] op_sel_hi:[1,0]
	v_pk_mov_b32 v[86:87], v[86:87], v[70:71] op_sel:[1,0] op_sel_hi:[1,0]
	s_mov_b64 exec, s[88:89]
	v_pk_mov_b32 v[88:89], v[88:89], v[90:91] op_sel:[1,0] op_sel_hi:[1,0]
	v_pk_mov_b32 v[90:91], v[90:91], v[92:93] op_sel:[1,0] op_sel_hi:[1,0]
	v_pk_mov_b32 v[92:93], v[92:93], v[94:95] op_sel:[1,0] op_sel_hi:[1,0]
	v_pk_mov_b32 v[94:95], v[94:95], v[70:71] op_sel:[1,0] op_sel_hi:[1,0]
	s_mov_b64 exec, s[90:91]
	v_pk_mov_b32 v[96:97], v[96:97], v[98:99] op_sel:[1,0] op_sel_hi:[1,0]
	v_pk_mov_b32 v[98:99], v[98:99], v[100:101] op_sel:[1,0] op_sel_hi:[1,0]
	v_pk_mov_b32 v[100:101], v[100:101], v[102:103] op_sel:[1,0] op_sel_hi:[1,0]
	v_pk_mov_b32 v[102:103], v[102:103], v[70:71] op_sel:[1,0] op_sel_hi:[1,0]
	s_lshl_b64 exec, s[78:79], s40
	s_add_i32 s40, s40, 1
	v_pk_mov_b32 v[18:19], v[54:55], v[54:55] op_sel:[0,1] op_sel_hi:[0,1]
	v_pk_mov_b32 v[20:21], v[56:57], v[56:57] op_sel:[0,1] op_sel_hi:[0,1]
	s_mov_b64 exec, -1
	v_max_u32_dpp v55, v72, v72 row_ror:1 row_mask:0xf bank_mask:0xf bound_ctrl:1
	v_max_u32_dpp v54, v80, v80 row_ror:1 row_mask:0xf bank_mask:0xf bound_ctrl:1
	v_max_u32_dpp v56, v88, v88 row_ror:1 row_mask:0xf bank_mask:0xf bound_ctrl:1
	v_max_u32_dpp v55, v55, v55 row_ror:2 row_mask:0xf bank_mask:0xf bound_ctrl:1
	v_max_u32_dpp v57, v96, v96 row_ror:1 row_mask:0xf bank_mask:0xf bound_ctrl:1
	v_max_u32_dpp v54, v54, v54 row_ror:2 row_mask:0xf bank_mask:0xf bound_ctrl:1
	v_max_u32_dpp v56, v56, v56 row_ror:2 row_mask:0xf bank_mask:0xf bound_ctrl:1
	v_max_u32_dpp v55, v55, v55 row_ror:4 row_mask:0xf bank_mask:0xf bound_ctrl:1
	v_max_u32_dpp v57, v57, v57 row_ror:2 row_mask:0xf bank_mask:0xf bound_ctrl:1
	v_max_u32_dpp v54, v54, v54 row_ror:4 row_mask:0xf bank_mask:0xf bound_ctrl:1
	v_max_u32_dpp v56, v56, v56 row_ror:4 row_mask:0xf bank_mask:0xf bound_ctrl:1
	v_max_u32_dpp v55, v55, v55 row_ror:8 row_mask:0xf bank_mask:0xf bound_ctrl:1
	v_max_u32_dpp v57, v57, v57 row_ror:4 row_mask:0xf bank_mask:0xf bound_ctrl:1
	v_max_u32_dpp v54, v54, v54 row_ror:8 row_mask:0xf bank_mask:0xf bound_ctrl:1
	v_max_u32_dpp v56, v56, v56 row_ror:8 row_mask:0xf bank_mask:0xf bound_ctrl:1
	v_max_u32_dpp v57, v57, v57 row_ror:8 row_mask:0xf bank_mask:0xf bound_ctrl:1
	v_cmp_eq_u32_e64 s[84:85], v72, v55
	v_cmp_eq_u32_e64 s[86:87], v80, v54
	v_cmp_eq_u32_e64 s[88:89], v88, v56
	v_cmp_eq_u32_e64 s[90:91], v96, v57
	s_mov_b64 exec, s[84:85]
	v_pk_mov_b32 v[72:73], v[72:73], v[74:75] op_sel:[1,0] op_sel_hi:[1,0]
	v_pk_mov_b32 v[74:75], v[74:75], v[76:77] op_sel:[1,0] op_sel_hi:[1,0]
	v_pk_mov_b32 v[76:77], v[76:77], v[78:79] op_sel:[1,0] op_sel_hi:[1,0]
	s_mov_b64 exec, s[86:87]
	v_pk_mov_b32 v[80:81], v[80:81], v[82:83] op_sel:[1,0] op_sel_hi:[1,0]
	v_pk_mov_b32 v[82:83], v[82:83], v[84:85] op_sel:[1,0] op_sel_hi:[1,0]
	v_pk_mov_b32 v[84:85], v[84:85], v[86:87] op_sel:[1,0] op_sel_hi:[1,0]
	s_mov_b64 exec, s[88:89]
	v_pk_mov_b32 v[88:89], v[88:89], v[90:91] op_sel:[1,0] op_sel_hi:[1,0]
	v_pk_mov_b32 v[90:91], v[90:91], v[92:93] op_sel:[1,0] op_sel_hi:[1,0]
	v_pk_mov_b32 v[92:93], v[92:93], v[94:95] op_sel:[1,0] op_sel_hi:[1,0]
	s_mov_b64 exec, s[90:91]
	v_pk_mov_b32 v[96:97], v[96:97], v[98:99] op_sel:[1,0] op_sel_hi:[1,0]
	v_pk_mov_b32 v[98:99], v[98:99], v[100:101] op_sel:[1,0] op_sel_hi:[1,0]
	v_pk_mov_b32 v[100:101], v[100:101], v[102:103] op_sel:[1,0] op_sel_hi:[1,0]
	s_lshl_b64 exec, s[78:79], s40
	s_add_i32 s40, s40, 1
	v_pk_mov_b32 v[18:19], v[54:55], v[54:55] op_sel:[0,1] op_sel_hi:[0,1]
	v_pk_mov_b32 v[20:21], v[56:57], v[56:57] op_sel:[0,1] op_sel_hi:[0,1]
	s_mov_b64 exec, -1
	v_max_u32_dpp v55, v72, v72 row_ror:1 row_mask:0xf bank_mask:0xf bound_ctrl:1
	v_max_u32_dpp v54, v80, v80 row_ror:1 row_mask:0xf bank_mask:0xf bound_ctrl:1
	v_max_u32_dpp v56, v88, v88 row_ror:1 row_mask:0xf bank_mask:0xf bound_ctrl:1
	v_max_u32_dpp v55, v55, v55 row_ror:2 row_mask:0xf bank_mask:0xf bound_ctrl:1
	v_max_u32_dpp v57, v96, v96 row_ror:1 row_mask:0xf bank_mask:0xf bound_ctrl:1
	v_max_u32_dpp v54, v54, v54 row_ror:2 row_mask:0xf bank_mask:0xf bound_ctrl:1
	v_max_u32_dpp v56, v56, v56 row_ror:2 row_mask:0xf bank_mask:0xf bound_ctrl:1
	v_max_u32_dpp v55, v55, v55 row_ror:4 row_mask:0xf bank_mask:0xf bound_ctrl:1
	v_max_u32_dpp v57, v57, v57 row_ror:2 row_mask:0xf bank_mask:0xf bound_ctrl:1
	v_max_u32_dpp v54, v54, v54 row_ror:4 row_mask:0xf bank_mask:0xf bound_ctrl:1
	v_max_u32_dpp v56, v56, v56 row_ror:4 row_mask:0xf bank_mask:0xf bound_ctrl:1
	v_max_u32_dpp v55, v55, v55 row_ror:8 row_mask:0xf bank_mask:0xf bound_ctrl:1
	v_max_u32_dpp v57, v57, v57 row_ror:4 row_mask:0xf bank_mask:0xf bound_ctrl:1
	v_max_u32_dpp v54, v54, v54 row_ror:8 row_mask:0xf bank_mask:0xf bound_ctrl:1
	v_max_u32_dpp v56, v56, v56 row_ror:8 row_mask:0xf bank_mask:0xf bound_ctrl:1
	v_max_u32_dpp v57, v57, v57 row_ror:8 row_mask:0xf bank_mask:0xf bound_ctrl:1
	v_cmp_eq_u32_e64 s[84:85], v72, v55
	v_cmp_eq_u32_e64 s[86:87], v80, v54
	v_cmp_eq_u32_e64 s[88:89], v88, v56
	v_cmp_eq_u32_e64 s[90:91], v96, v57
	s_mov_b64 exec, s[84:85]
	v_pk_mov_b32 v[72:73], v[72:73], v[74:75] op_sel:[1,0] op_sel_hi:[1,0]
	v_pk_mov_b32 v[74:75], v[74:75], v[76:77] op_sel:[1,0] op_sel_hi:[1,0]
	v_pk_mov_b32 v[76:77], v[76:77], v[78:79] op_sel:[1,0] op_sel_hi:[1,0]
	s_mov_b64 exec, s[86:87]
	v_pk_mov_b32 v[80:81], v[80:81], v[82:83] op_sel:[1,0] op_sel_hi:[1,0]
	v_pk_mov_b32 v[82:83], v[82:83], v[84:85] op_sel:[1,0] op_sel_hi:[1,0]
	v_pk_mov_b32 v[84:85], v[84:85], v[86:87] op_sel:[1,0] op_sel_hi:[1,0]
	s_mov_b64 exec, s[88:89]
	v_pk_mov_b32 v[88:89], v[88:89], v[90:91] op_sel:[1,0] op_sel_hi:[1,0]
	v_pk_mov_b32 v[90:91], v[90:91], v[92:93] op_sel:[1,0] op_sel_hi:[1,0]
	v_pk_mov_b32 v[92:93], v[92:93], v[94:95] op_sel:[1,0] op_sel_hi:[1,0]
	s_mov_b64 exec, s[90:91]
	v_pk_mov_b32 v[96:97], v[96:97], v[98:99] op_sel:[1,0] op_sel_hi:[1,0]
	v_pk_mov_b32 v[98:99], v[98:99], v[100:101] op_sel:[1,0] op_sel_hi:[1,0]
	v_pk_mov_b32 v[100:101], v[100:101], v[102:103] op_sel:[1,0] op_sel_hi:[1,0]
	s_lshl_b64 exec, s[78:79], s40
	s_add_i32 s40, s40, 1
	v_pk_mov_b32 v[18:19], v[54:55], v[54:55] op_sel:[0,1] op_sel_hi:[0,1]
	v_pk_mov_b32 v[20:21], v[56:57], v[56:57] op_sel:[0,1] op_sel_hi:[0,1]
	s_mov_b64 exec, -1
	v_max_u32_dpp v55, v72, v72 row_ror:1 row_mask:0xf bank_mask:0xf bound_ctrl:1
	v_max_u32_dpp v54, v80, v80 row_ror:1 row_mask:0xf bank_mask:0xf bound_ctrl:1
	v_max_u32_dpp v56, v88, v88 row_ror:1 row_mask:0xf bank_mask:0xf bound_ctrl:1
	v_max_u32_dpp v55, v55, v55 row_ror:2 row_mask:0xf bank_mask:0xf bound_ctrl:1
	v_max_u32_dpp v57, v96, v96 row_ror:1 row_mask:0xf bank_mask:0xf bound_ctrl:1
	v_max_u32_dpp v54, v54, v54 row_ror:2 row_mask:0xf bank_mask:0xf bound_ctrl:1
	v_max_u32_dpp v56, v56, v56 row_ror:2 row_mask:0xf bank_mask:0xf bound_ctrl:1
	v_max_u32_dpp v55, v55, v55 row_ror:4 row_mask:0xf bank_mask:0xf bound_ctrl:1
	v_max_u32_dpp v57, v57, v57 row_ror:2 row_mask:0xf bank_mask:0xf bound_ctrl:1
	v_max_u32_dpp v54, v54, v54 row_ror:4 row_mask:0xf bank_mask:0xf bound_ctrl:1
	v_max_u32_dpp v56, v56, v56 row_ror:4 row_mask:0xf bank_mask:0xf bound_ctrl:1
	v_max_u32_dpp v55, v55, v55 row_ror:8 row_mask:0xf bank_mask:0xf bound_ctrl:1
	v_max_u32_dpp v57, v57, v57 row_ror:4 row_mask:0xf bank_mask:0xf bound_ctrl:1
	v_max_u32_dpp v54, v54, v54 row_ror:8 row_mask:0xf bank_mask:0xf bound_ctrl:1
	v_max_u32_dpp v56, v56, v56 row_ror:8 row_mask:0xf bank_mask:0xf bound_ctrl:1
	v_max_u32_dpp v57, v57, v57 row_ror:8 row_mask:0xf bank_mask:0xf bound_ctrl:1
	v_cmp_eq_u32_e64 s[84:85], v72, v55
	v_cmp_eq_u32_e64 s[86:87], v80, v54
	v_cmp_eq_u32_e64 s[88:89], v88, v56
	v_cmp_eq_u32_e64 s[90:91], v96, v57
	s_mov_b64 exec, s[84:85]
	v_pk_mov_b32 v[72:73], v[72:73], v[74:75] op_sel:[1,0] op_sel_hi:[1,0]
	v_pk_mov_b32 v[74:75], v[74:75], v[76:77] op_sel:[1,0] op_sel_hi:[1,0]
	s_mov_b64 exec, s[86:87]
	v_pk_mov_b32 v[80:81], v[80:81], v[82:83] op_sel:[1,0] op_sel_hi:[1,0]
	v_pk_mov_b32 v[82:83], v[82:83], v[84:85] op_sel:[1,0] op_sel_hi:[1,0]
	s_mov_b64 exec, s[88:89]
	v_pk_mov_b32 v[88:89], v[88:89], v[90:91] op_sel:[1,0] op_sel_hi:[1,0]
	v_pk_mov_b32 v[90:91], v[90:91], v[92:93] op_sel:[1,0] op_sel_hi:[1,0]
	s_mov_b64 exec, s[90:91]
	v_pk_mov_b32 v[96:97], v[96:97], v[98:99] op_sel:[1,0] op_sel_hi:[1,0]
	v_pk_mov_b32 v[98:99], v[98:99], v[100:101] op_sel:[1,0] op_sel_hi:[1,0]
	s_lshl_b64 exec, s[78:79], s40
	s_add_i32 s40, s40, 1
	v_pk_mov_b32 v[18:19], v[54:55], v[54:55] op_sel:[0,1] op_sel_hi:[0,1]
	v_pk_mov_b32 v[20:21], v[56:57], v[56:57] op_sel:[0,1] op_sel_hi:[0,1]
	s_mov_b64 exec, -1
	v_max_u32_dpp v55, v72, v72 row_ror:1 row_mask:0xf bank_mask:0xf bound_ctrl:1
	v_max_u32_dpp v54, v80, v80 row_ror:1 row_mask:0xf bank_mask:0xf bound_ctrl:1
	v_max_u32_dpp v56, v88, v88 row_ror:1 row_mask:0xf bank_mask:0xf bound_ctrl:1
	v_max_u32_dpp v55, v55, v55 row_ror:2 row_mask:0xf bank_mask:0xf bound_ctrl:1
	v_max_u32_dpp v57, v96, v96 row_ror:1 row_mask:0xf bank_mask:0xf bound_ctrl:1
	v_max_u32_dpp v54, v54, v54 row_ror:2 row_mask:0xf bank_mask:0xf bound_ctrl:1
	v_max_u32_dpp v56, v56, v56 row_ror:2 row_mask:0xf bank_mask:0xf bound_ctrl:1
	v_max_u32_dpp v55, v55, v55 row_ror:4 row_mask:0xf bank_mask:0xf bound_ctrl:1
	v_max_u32_dpp v57, v57, v57 row_ror:2 row_mask:0xf bank_mask:0xf bound_ctrl:1
	v_max_u32_dpp v54, v54, v54 row_ror:4 row_mask:0xf bank_mask:0xf bound_ctrl:1
	v_max_u32_dpp v56, v56, v56 row_ror:4 row_mask:0xf bank_mask:0xf bound_ctrl:1
	v_max_u32_dpp v55, v55, v55 row_ror:8 row_mask:0xf bank_mask:0xf bound_ctrl:1
	v_max_u32_dpp v57, v57, v57 row_ror:4 row_mask:0xf bank_mask:0xf bound_ctrl:1
	v_max_u32_dpp v54, v54, v54 row_ror:8 row_mask:0xf bank_mask:0xf bound_ctrl:1
	v_max_u32_dpp v56, v56, v56 row_ror:8 row_mask:0xf bank_mask:0xf bound_ctrl:1
	v_max_u32_dpp v57, v57, v57 row_ror:8 row_mask:0xf bank_mask:0xf bound_ctrl:1
	v_cmp_eq_u32_e64 s[84:85], v72, v55
	v_cmp_eq_u32_e64 s[86:87], v80, v54
	v_cmp_eq_u32_e64 s[88:89], v88, v56
	v_cmp_eq_u32_e64 s[90:91], v96, v57
	s_mov_b64 exec, s[84:85]
	v_pk_mov_b32 v[72:73], v[72:73], v[74:75] op_sel:[1,0] op_sel_hi:[1,0]
	v_pk_mov_b32 v[74:75], v[74:75], v[76:77] op_sel:[1,0] op_sel_hi:[1,0]
	s_mov_b64 exec, s[86:87]
	v_pk_mov_b32 v[80:81], v[80:81], v[82:83] op_sel:[1,0] op_sel_hi:[1,0]
	v_pk_mov_b32 v[82:83], v[82:83], v[84:85] op_sel:[1,0] op_sel_hi:[1,0]
	s_mov_b64 exec, s[88:89]
	v_pk_mov_b32 v[88:89], v[88:89], v[90:91] op_sel:[1,0] op_sel_hi:[1,0]
	v_pk_mov_b32 v[90:91], v[90:91], v[92:93] op_sel:[1,0] op_sel_hi:[1,0]
	s_mov_b64 exec, s[90:91]
	v_pk_mov_b32 v[96:97], v[96:97], v[98:99] op_sel:[1,0] op_sel_hi:[1,0]
	v_pk_mov_b32 v[98:99], v[98:99], v[100:101] op_sel:[1,0] op_sel_hi:[1,0]
	s_lshl_b64 exec, s[78:79], s40
	s_add_i32 s40, s40, 1
	v_pk_mov_b32 v[18:19], v[54:55], v[54:55] op_sel:[0,1] op_sel_hi:[0,1]
	v_pk_mov_b32 v[20:21], v[56:57], v[56:57] op_sel:[0,1] op_sel_hi:[0,1]
	s_mov_b64 exec, -1
	v_max_u32_dpp v55, v72, v72 row_ror:1 row_mask:0xf bank_mask:0xf bound_ctrl:1
	v_max_u32_dpp v54, v80, v80 row_ror:1 row_mask:0xf bank_mask:0xf bound_ctrl:1
	v_max_u32_dpp v56, v88, v88 row_ror:1 row_mask:0xf bank_mask:0xf bound_ctrl:1
	v_max_u32_dpp v55, v55, v55 row_ror:2 row_mask:0xf bank_mask:0xf bound_ctrl:1
	v_max_u32_dpp v57, v96, v96 row_ror:1 row_mask:0xf bank_mask:0xf bound_ctrl:1
	v_max_u32_dpp v54, v54, v54 row_ror:2 row_mask:0xf bank_mask:0xf bound_ctrl:1
	v_max_u32_dpp v56, v56, v56 row_ror:2 row_mask:0xf bank_mask:0xf bound_ctrl:1
	v_max_u32_dpp v55, v55, v55 row_ror:4 row_mask:0xf bank_mask:0xf bound_ctrl:1
	v_max_u32_dpp v57, v57, v57 row_ror:2 row_mask:0xf bank_mask:0xf bound_ctrl:1
	v_max_u32_dpp v54, v54, v54 row_ror:4 row_mask:0xf bank_mask:0xf bound_ctrl:1
	v_max_u32_dpp v56, v56, v56 row_ror:4 row_mask:0xf bank_mask:0xf bound_ctrl:1
	v_max_u32_dpp v55, v55, v55 row_ror:8 row_mask:0xf bank_mask:0xf bound_ctrl:1
	v_max_u32_dpp v57, v57, v57 row_ror:4 row_mask:0xf bank_mask:0xf bound_ctrl:1
	v_max_u32_dpp v54, v54, v54 row_ror:8 row_mask:0xf bank_mask:0xf bound_ctrl:1
	v_max_u32_dpp v56, v56, v56 row_ror:8 row_mask:0xf bank_mask:0xf bound_ctrl:1
	v_max_u32_dpp v57, v57, v57 row_ror:8 row_mask:0xf bank_mask:0xf bound_ctrl:1
	v_cmp_eq_u32_e64 s[84:85], v72, v55
	v_cmp_eq_u32_e64 s[86:87], v80, v54
	v_cmp_eq_u32_e64 s[88:89], v88, v56
	v_cmp_eq_u32_e64 s[90:91], v96, v57
	s_mov_b64 exec, s[84:85]
	v_pk_mov_b32 v[72:73], v[72:73], v[74:75] op_sel:[1,0] op_sel_hi:[1,0]
	s_mov_b64 exec, s[86:87]
	v_pk_mov_b32 v[80:81], v[80:81], v[82:83] op_sel:[1,0] op_sel_hi:[1,0]
	s_mov_b64 exec, s[88:89]
	v_pk_mov_b32 v[88:89], v[88:89], v[90:91] op_sel:[1,0] op_sel_hi:[1,0]
	s_mov_b64 exec, s[90:91]
	v_pk_mov_b32 v[96:97], v[96:97], v[98:99] op_sel:[1,0] op_sel_hi:[1,0]
	s_lshl_b64 exec, s[78:79], s40
	s_add_i32 s40, s40, 1
	v_pk_mov_b32 v[18:19], v[54:55], v[54:55] op_sel:[0,1] op_sel_hi:[0,1]
	v_pk_mov_b32 v[20:21], v[56:57], v[56:57] op_sel:[0,1] op_sel_hi:[0,1]
	s_mov_b64 exec, -1
	v_max_u32_dpp v55, v72, v72 row_ror:1 row_mask:0xf bank_mask:0xf bound_ctrl:1
	v_max_u32_dpp v54, v80, v80 row_ror:1 row_mask:0xf bank_mask:0xf bound_ctrl:1
	v_max_u32_dpp v56, v88, v88 row_ror:1 row_mask:0xf bank_mask:0xf bound_ctrl:1
	v_max_u32_dpp v55, v55, v55 row_ror:2 row_mask:0xf bank_mask:0xf bound_ctrl:1
	v_max_u32_dpp v57, v96, v96 row_ror:1 row_mask:0xf bank_mask:0xf bound_ctrl:1
	v_max_u32_dpp v54, v54, v54 row_ror:2 row_mask:0xf bank_mask:0xf bound_ctrl:1
	v_max_u32_dpp v56, v56, v56 row_ror:2 row_mask:0xf bank_mask:0xf bound_ctrl:1
	v_max_u32_dpp v55, v55, v55 row_ror:4 row_mask:0xf bank_mask:0xf bound_ctrl:1
	v_max_u32_dpp v57, v57, v57 row_ror:2 row_mask:0xf bank_mask:0xf bound_ctrl:1
	v_max_u32_dpp v54, v54, v54 row_ror:4 row_mask:0xf bank_mask:0xf bound_ctrl:1
	v_max_u32_dpp v56, v56, v56 row_ror:4 row_mask:0xf bank_mask:0xf bound_ctrl:1
	v_max_u32_dpp v55, v55, v55 row_ror:8 row_mask:0xf bank_mask:0xf bound_ctrl:1
	v_max_u32_dpp v57, v57, v57 row_ror:4 row_mask:0xf bank_mask:0xf bound_ctrl:1
	v_max_u32_dpp v54, v54, v54 row_ror:8 row_mask:0xf bank_mask:0xf bound_ctrl:1
	v_max_u32_dpp v56, v56, v56 row_ror:8 row_mask:0xf bank_mask:0xf bound_ctrl:1
	v_max_u32_dpp v57, v57, v57 row_ror:8 row_mask:0xf bank_mask:0xf bound_ctrl:1
	v_cmp_eq_u32_e64 s[84:85], v72, v55
	v_cmp_eq_u32_e64 s[86:87], v80, v54
	v_cmp_eq_u32_e64 s[88:89], v88, v56
	v_cmp_eq_u32_e64 s[90:91], v96, v57
	s_mov_b64 exec, s[84:85]
	v_pk_mov_b32 v[72:73], v[72:73], v[74:75] op_sel:[1,0] op_sel_hi:[1,0]
	s_mov_b64 exec, s[86:87]
	v_pk_mov_b32 v[80:81], v[80:81], v[82:83] op_sel:[1,0] op_sel_hi:[1,0]
	s_mov_b64 exec, s[88:89]
	v_pk_mov_b32 v[88:89], v[88:89], v[90:91] op_sel:[1,0] op_sel_hi:[1,0]
	s_mov_b64 exec, s[90:91]
	v_pk_mov_b32 v[96:97], v[96:97], v[98:99] op_sel:[1,0] op_sel_hi:[1,0]
	s_lshl_b64 exec, s[78:79], s40
	s_add_i32 s40, s40, 1
	v_pk_mov_b32 v[18:19], v[54:55], v[54:55] op_sel:[0,1] op_sel_hi:[0,1]
	v_pk_mov_b32 v[20:21], v[56:57], v[56:57] op_sel:[0,1] op_sel_hi:[0,1]
	s_mov_b64 exec, -1
	v_max_u32_dpp v55, v72, v72 row_ror:1 row_mask:0xf bank_mask:0xf bound_ctrl:1
	v_max_u32_dpp v54, v80, v80 row_ror:1 row_mask:0xf bank_mask:0xf bound_ctrl:1
	v_max_u32_dpp v56, v88, v88 row_ror:1 row_mask:0xf bank_mask:0xf bound_ctrl:1
	v_max_u32_dpp v55, v55, v55 row_ror:2 row_mask:0xf bank_mask:0xf bound_ctrl:1
	v_max_u32_dpp v57, v96, v96 row_ror:1 row_mask:0xf bank_mask:0xf bound_ctrl:1
	v_max_u32_dpp v54, v54, v54 row_ror:2 row_mask:0xf bank_mask:0xf bound_ctrl:1
	v_max_u32_dpp v56, v56, v56 row_ror:2 row_mask:0xf bank_mask:0xf bound_ctrl:1
	v_max_u32_dpp v55, v55, v55 row_ror:4 row_mask:0xf bank_mask:0xf bound_ctrl:1
	v_max_u32_dpp v57, v57, v57 row_ror:2 row_mask:0xf bank_mask:0xf bound_ctrl:1
	v_max_u32_dpp v54, v54, v54 row_ror:4 row_mask:0xf bank_mask:0xf bound_ctrl:1
	v_max_u32_dpp v56, v56, v56 row_ror:4 row_mask:0xf bank_mask:0xf bound_ctrl:1
	v_max_u32_dpp v55, v55, v55 row_ror:8 row_mask:0xf bank_mask:0xf bound_ctrl:1
	v_max_u32_dpp v57, v57, v57 row_ror:4 row_mask:0xf bank_mask:0xf bound_ctrl:1
	v_max_u32_dpp v54, v54, v54 row_ror:8 row_mask:0xf bank_mask:0xf bound_ctrl:1
	v_max_u32_dpp v56, v56, v56 row_ror:8 row_mask:0xf bank_mask:0xf bound_ctrl:1
	v_max_u32_dpp v57, v57, v57 row_ror:8 row_mask:0xf bank_mask:0xf bound_ctrl:1
	s_lshl_b64 exec, s[78:79], s40
	v_pk_mov_b32 v[18:19], v[54:55], v[54:55] op_sel:[0,1] op_sel_hi:[0,1]
	v_pk_mov_b32 v[20:21], v[56:57], v[56:57] op_sel:[0,1] op_sel_hi:[0,1]
	s_mov_b64 exec, -1
	ds_read_b128 v[22:25], v184 offset:34816
	ds_read_b128 v[26:29], v184 offset:34880
	s_waitcnt vmcnt(0) lgkmcnt(1)
	v_mfma_f32_16x16x32_bf16 v[22:25], v[12:15], v[22:25], 0
	s_waitcnt lgkmcnt(0)
	v_mfma_f32_16x16x32_bf16 v[22:25], v[8:11], v[26:29], v[22:25]
	ds_read_b128 v[26:29], v184 offset:34944
	s_waitcnt lgkmcnt(0)
	v_mfma_f32_16x16x32_bf16 v[22:25], v[4:7], v[26:29], v[22:25]
	ds_read_b128 v[26:29], v184 offset:35008
	s_waitcnt lgkmcnt(0)
	v_mfma_f32_16x16x32_bf16 v[22:25], v[0:3], v[26:29], v[22:25]
	ds_read_b128 v[26:29], v184 offset:39168
	ds_read_b128 v[30:33], v184 offset:39232
	s_waitcnt lgkmcnt(1)
	v_mfma_f32_16x16x32_bf16 v[26:29], v[12:15], v[26:29], 0
	s_waitcnt lgkmcnt(0)
	v_mfma_f32_16x16x32_bf16 v[26:29], v[8:11], v[30:33], v[26:29]
	ds_read_b128 v[30:33], v184 offset:39296
	ds_read_b128 v[34:37], v184 offset:39360
	s_waitcnt lgkmcnt(1)
	v_mfma_f32_16x16x32_bf16 v[26:29], v[4:7], v[30:33], v[26:29]
	s_waitcnt lgkmcnt(0)
	v_mfma_f32_16x16x32_bf16 v[26:29], v[0:3], v[34:37], v[26:29]
	ds_read_b128 v[30:33], v184 offset:43520
	ds_read_b128 v[34:37], v184 offset:43584
	s_waitcnt lgkmcnt(1)
	v_mfma_f32_16x16x32_bf16 v[30:33], v[12:15], v[30:33], 0
	s_waitcnt lgkmcnt(0)
	v_mfma_f32_16x16x32_bf16 v[30:33], v[8:11], v[34:37], v[30:33]
	ds_read_b128 v[34:37], v184 offset:43648
	ds_read_b128 v[38:41], v184 offset:43712
	s_waitcnt lgkmcnt(1)
	v_mfma_f32_16x16x32_bf16 v[30:33], v[4:7], v[34:37], v[30:33]
	s_waitcnt lgkmcnt(0)
	v_mfma_f32_16x16x32_bf16 v[30:33], v[0:3], v[38:41], v[30:33]
	ds_read_b128 v[34:37], v184 offset:47872
	ds_read_b128 v[38:41], v184 offset:47936
	s_waitcnt lgkmcnt(1)
	v_mfma_f32_16x16x32_bf16 v[34:37], v[12:15], v[34:37], 0
	s_waitcnt lgkmcnt(0)
	v_mfma_f32_16x16x32_bf16 v[34:37], v[8:11], v[38:41], v[34:37]
	ds_read_b128 v[38:41], v184 offset:48000
	ds_read_b128 v[42:45], v184 offset:48064
	s_waitcnt lgkmcnt(1)
	v_mfma_f32_16x16x32_bf16 v[34:37], v[4:7], v[38:41], v[34:37]
	s_waitcnt lgkmcnt(0)
	v_mfma_f32_16x16x32_bf16 v[34:37], v[0:3], v[42:45], v[34:37]
	ds_read_b128 v[38:41], v184 offset:52224
	ds_read_b128 v[42:45], v184 offset:52288
	s_waitcnt lgkmcnt(1)
	v_mfma_f32_16x16x32_bf16 v[38:41], v[12:15], v[38:41], 0
	s_waitcnt lgkmcnt(0)
	v_mfma_f32_16x16x32_bf16 v[38:41], v[8:11], v[42:45], v[38:41]
	ds_read_b128 v[42:45], v184 offset:52352
	ds_read_b128 v[46:49], v184 offset:52416
	s_waitcnt lgkmcnt(1)
	v_mfma_f32_16x16x32_bf16 v[38:41], v[4:7], v[42:45], v[38:41]
	s_waitcnt lgkmcnt(0)
	v_mfma_f32_16x16x32_bf16 v[38:41], v[0:3], v[46:49], v[38:41]
	ds_read_b128 v[42:45], v184 offset:56576
	ds_read_b128 v[46:49], v184 offset:56640
	s_waitcnt lgkmcnt(1)
	v_mfma_f32_16x16x32_bf16 v[42:45], v[12:15], v[42:45], 0
	s_waitcnt lgkmcnt(0)
	v_mfma_f32_16x16x32_bf16 v[42:45], v[8:11], v[46:49], v[42:45]
	ds_read_b128 v[46:49], v184 offset:56704
	ds_read_b128 v[50:53], v184 offset:56768
	s_waitcnt lgkmcnt(1)
	v_mfma_f32_16x16x32_bf16 v[42:45], v[4:7], v[46:49], v[42:45]
	s_waitcnt lgkmcnt(0)
	v_mfma_f32_16x16x32_bf16 v[42:45], v[0:3], v[50:53], v[42:45]
	ds_read_b128 v[46:49], v184 offset:60928
	ds_read_b128 v[50:53], v184 offset:60992
	s_waitcnt lgkmcnt(1)
	v_mfma_f32_16x16x32_bf16 v[46:49], v[12:15], v[46:49], 0
	s_waitcnt lgkmcnt(0)
	v_mfma_f32_16x16x32_bf16 v[46:49], v[8:11], v[50:53], v[46:49]
	ds_read_b128 v[50:53], v184 offset:61056
	ds_read_b128 v[54:57], v184 offset:61120
	s_waitcnt lgkmcnt(1)
	v_mfma_f32_16x16x32_bf16 v[46:49], v[4:7], v[50:53], v[46:49]
	s_waitcnt lgkmcnt(0)
	v_mfma_f32_16x16x32_bf16 v[46:49], v[0:3], v[54:57], v[46:49]
	ds_read_b128 v[50:53], v184 offset:65280
	ds_read_b128 v[54:57], v184 offset:65344
	s_waitcnt lgkmcnt(1)
	v_mfma_f32_16x16x32_bf16 v[12:15], v[12:15], v[50:53], 0
	s_waitcnt lgkmcnt(0)
	v_mfma_f32_16x16x32_bf16 v[8:11], v[8:11], v[54:57], v[12:15]
	s_nop 5
	ds_read_b128 v[12:15], v184 offset:65408
	ds_read_b128 v[50:53], v184 offset:65472
	s_waitcnt lgkmcnt(1)
	v_mfma_f32_16x16x32_bf16 v[4:7], v[4:7], v[12:15], v[8:11]
	s_waitcnt lgkmcnt(0)
	v_mfma_f32_16x16x32_bf16 v[0:3], v[0:3], v[50:53], v[4:7]
	s_nop 7
	s_mov_b32 s40, 0
	v_ashrrev_i32_e32 v4, 31, v3
	v_bitop3_b32 v3, v3, v4, v217 bitop3:0x1e
	v_and_or_b32 v3, v3, s67, v178
	v_ashrrev_i32_e32 v4, 31, v49
	v_bitop3_b32 v4, v49, v4, v217 bitop3:0x1e
	v_and_or_b32 v49, v4, s67, v177
	v_ashrrev_i32_e32 v4, 31, v45
	v_bitop3_b32 v4, v45, v4, v217 bitop3:0x1e
	v_and_or_b32 v45, v4, s67, v176
	v_ashrrev_i32_e32 v4, 31, v41
	v_bitop3_b32 v4, v41, v4, v217 bitop3:0x1e
	v_and_or_b32 v41, v4, s67, v175
	v_ashrrev_i32_e32 v4, 31, v37
	v_bitop3_b32 v4, v37, v4, v217 bitop3:0x1e
	v_and_or_b32 v37, v4, s67, v170
	v_ashrrev_i32_e32 v4, 31, v33
	v_bitop3_b32 v4, v33, v4, v217 bitop3:0x1e
	v_and_or_b32 v50, v4, s67, v181
	v_ashrrev_i32_e32 v4, 31, v29
	v_bitop3_b32 v4, v29, v4, v217 bitop3:0x1e
	v_and_or_b32 v51, v4, s67, v180
	v_ashrrev_i32_e32 v4, 31, v25
	v_bitop3_b32 v4, v25, v4, v217 bitop3:0x1e
	v_and_or_b32 v52, v4, s67, v179
	v_ashrrev_i32_e32 v4, 31, v2
	v_bitop3_b32 v2, v2, v4, v217 bitop3:0x1e
	v_and_or_b32 v2, v2, s67, v178
	v_ashrrev_i32_e32 v4, 31, v48
	v_bitop3_b32 v4, v48, v4, v217 bitop3:0x1e
	v_and_or_b32 v29, v4, s67, v177
	v_ashrrev_i32_e32 v4, 31, v44
	v_bitop3_b32 v4, v44, v4, v217 bitop3:0x1e
	v_and_or_b32 v33, v4, s67, v176
	v_ashrrev_i32_e32 v4, 31, v40
	v_bitop3_b32 v4, v40, v4, v217 bitop3:0x1e
	v_and_or_b32 v40, v4, s67, v175
	v_ashrrev_i32_e32 v4, 31, v36
	v_bitop3_b32 v4, v36, v4, v217 bitop3:0x1e
	v_and_or_b32 v36, v4, s67, v170
	v_ashrrev_i32_e32 v4, 31, v32
	v_bitop3_b32 v4, v32, v4, v217 bitop3:0x1e
	v_and_or_b32 v32, v4, s67, v181
	v_ashrrev_i32_e32 v4, 31, v28
	v_bitop3_b32 v4, v28, v4, v217 bitop3:0x1e
	v_and_or_b32 v28, v4, s67, v180
	v_ashrrev_i32_e32 v4, 31, v24
	v_bitop3_b32 v4, v24, v4, v217 bitop3:0x1e
	v_and_or_b32 v44, v4, s67, v179
	v_ashrrev_i32_e32 v4, 31, v1
	v_bitop3_b32 v1, v1, v4, v217 bitop3:0x1e
	v_and_or_b32 v1, v1, s67, v178
	v_ashrrev_i32_e32 v4, 31, v47
	v_bitop3_b32 v4, v47, v4, v217 bitop3:0x1e
	v_and_or_b32 v12, v4, s67, v177
	v_ashrrev_i32_e32 v4, 31, v43
	v_bitop3_b32 v4, v43, v4, v217 bitop3:0x1e
	v_and_or_b32 v13, v4, s67, v176
	v_ashrrev_i32_e32 v4, 31, v39
	v_bitop3_b32 v4, v39, v4, v217 bitop3:0x1e
	v_and_or_b32 v14, v4, s67, v175
	v_ashrrev_i32_e32 v4, 31, v35
	v_bitop3_b32 v4, v35, v4, v217 bitop3:0x1e
	v_and_or_b32 v15, v4, s67, v170
	v_max_u32_e32 v35, v41, v45
	v_ashrrev_i32_e32 v4, 31, v31
	v_bitop3_b32 v4, v31, v4, v217 bitop3:0x1e
	v_and_or_b32 v24, v4, s67, v181
	v_max_u32_e32 v31, v29, v2
	v_ashrrev_i32_e32 v4, 31, v27
	v_bitop3_b32 v4, v27, v4, v217 bitop3:0x1e
	v_and_or_b32 v25, v4, s67, v180
	v_min_u32_e32 v2, v29, v2
	v_ashrrev_i32_e32 v4, 31, v23
	v_bitop3_b32 v4, v23, v4, v217 bitop3:0x1e
	v_and_or_b32 v23, v4, s67, v179
	v_ashrrev_i32_e32 v4, 31, v0
	v_bitop3_b32 v0, v0, v4, v217 bitop3:0x1e
	v_and_or_b32 v0, v0, s67, v178
	v_ashrrev_i32_e32 v4, 31, v46
	v_bitop3_b32 v4, v46, v4, v217 bitop3:0x1e
	v_and_or_b32 v4, v4, s67, v177
	v_ashrrev_i32_e32 v5, 31, v42
	v_bitop3_b32 v5, v42, v5, v217 bitop3:0x1e
	v_and_or_b32 v5, v5, s67, v176
	v_ashrrev_i32_e32 v6, 31, v38
	v_bitop3_b32 v6, v38, v6, v217 bitop3:0x1e
	v_and_or_b32 v6, v6, s67, v175
	v_ashrrev_i32_e32 v7, 31, v34
	v_bitop3_b32 v7, v34, v7, v217 bitop3:0x1e
	v_and_or_b32 v7, v7, s67, v170
	v_ashrrev_i32_e32 v8, 31, v30
	v_bitop3_b32 v8, v30, v8, v217 bitop3:0x1e
	v_and_or_b32 v8, v8, s67, v181
	v_ashrrev_i32_e32 v9, 31, v26
	v_bitop3_b32 v9, v26, v9, v217 bitop3:0x1e
	v_and_or_b32 v9, v9, s67, v180
	v_ashrrev_i32_e32 v10, 31, v22
	v_bitop3_b32 v10, v22, v10, v217 bitop3:0x1e
	v_and_or_b32 v10, v10, s67, v179
	v_max_u32_e32 v11, v10, v9
	v_min_u32_e32 v9, v10, v9
	v_max_u32_e32 v10, v8, v7
	v_min_u32_e32 v7, v8, v7
	v_max_u32_e32 v8, v6, v5
	v_min_u32_e32 v5, v6, v5
	v_max_u32_e32 v6, v4, v0
	v_min_u32_e32 v0, v4, v0
	v_max_u32_e32 v22, v11, v10
	v_min_u32_e32 v4, v11, v10
	v_max_u32_e32 v10, v9, v7
	v_min_u32_e32 v7, v9, v7
	v_max_u32_e32 v9, v8, v6
	v_min_u32_e32 v6, v8, v6
	v_max_u32_e32 v8, v5, v0
	v_min_u32_e32 v0, v5, v0
	v_max_u32_e32 v5, v10, v4
	v_min_u32_e32 v10, v10, v4
	v_max_u32_e32 v11, v8, v6
	v_min_u32_e32 v6, v8, v6
	v_max_u32_e32 v4, v22, v9
	v_min_u32_e32 v8, v22, v9
	v_max_u32_e32 v9, v5, v11
	v_min_u32_e32 v11, v5, v11
	v_max_u32_e32 v22, v10, v6
	v_min_u32_e32 v26, v10, v6
	v_max_u32_e32 v6, v7, v0
	v_min_u32_e32 v5, v7, v0
	v_max_u32_e32 v0, v22, v8
	v_min_u32_e32 v10, v22, v8
	v_max_u32_e32 v22, v6, v11
	v_min_u32_e32 v11, v6, v11
	v_max_u32_e32 v6, v9, v0
	v_min_u32_e32 v7, v9, v0
	v_max_u32_e32 v8, v22, v10
	v_min_u32_e32 v9, v22, v10
	v_max_u32_e32 v0, v23, v25
	v_min_u32_e32 v22, v23, v25
	v_max_u32_e32 v23, v24, v15
	v_min_u32_e32 v15, v24, v15
	v_max_u32_e32 v24, v14, v13
	v_min_u32_e32 v13, v14, v13
	v_max_u32_e32 v14, v12, v1
	v_min_u32_e32 v1, v12, v1
	v_max_u32_e32 v25, v0, v23
	v_min_u32_e32 v0, v0, v23
	v_max_u32_e32 v12, v22, v15
	v_min_u32_e32 v15, v22, v15
	v_max_u32_e32 v22, v24, v14
	v_min_u32_e32 v14, v24, v14
	v_max_u32_e32 v23, v13, v1
	v_min_u32_e32 v1, v13, v1
	v_max_u32_e32 v13, v12, v0
	v_min_u32_e32 v0, v12, v0
	v_max_u32_e32 v24, v23, v14
	v_min_u32_e32 v14, v23, v14
	v_max_u32_e32 v12, v25, v22
	v_min_u32_e32 v22, v25, v22
	v_max_u32_e32 v23, v13, v24
	v_min_u32_e32 v24, v13, v24
	v_max_u32_e32 v25, v0, v14
	v_min_u32_e32 v0, v0, v14
	v_max_u32_e32 v14, v15, v1
	v_max_u32_e32 v10, v11, v26
	v_min_u32_e32 v11, v11, v26
	v_min_u32_e32 v13, v15, v1
	v_max_u32_e32 v1, v25, v22
	v_min_u32_e32 v25, v25, v22
	v_max_u32_e32 v26, v14, v24
	v_min_u32_e32 v27, v14, v24
	v_max_u32_e32 v14, v23, v1
	v_min_u32_e32 v15, v23, v1
	v_max_u32_e32 v22, v26, v25
	v_min_u32_e32 v23, v26, v25
	v_max_u32_e32 v24, v27, v0
	v_min_u32_e32 v25, v27, v0
	v_max_u32_e32 v0, v44, v28
	v_min_u32_e32 v1, v44, v28
	v_max_u32_e32 v26, v32, v36
	v_min_u32_e32 v27, v32, v36
	v_max_u32_e32 v28, v40, v33
	v_min_u32_e32 v30, v40, v33
	v_max_u32_e32 v29, v0, v26
	v_min_u32_e32 v0, v0, v26
	v_max_u32_e32 v26, v1, v27
	v_min_u32_e32 v1, v1, v27
	v_max_u32_e32 v27, v28, v31
	v_min_u32_e32 v28, v28, v31
	v_max_u32_e32 v31, v30, v2
	v_min_u32_e32 v2, v30, v2
	v_max_u32_e32 v30, v26, v0
	v_min_u32_e32 v0, v26, v0
	v_max_u32_e32 v32, v31, v28
	v_min_u32_e32 v28, v31, v28
	v_max_u32_e32 v26, v29, v27
	v_min_u32_e32 v29, v29, v27
	v_max_u32_e32 v31, v30, v32
	v_min_u32_e32 v30, v30, v32
	v_max_u32_e32 v32, v0, v28
	v_min_u32_e32 v0, v0, v28
	v_max_u32_e32 v28, v1, v2
	v_min_u32_e32 v27, v1, v2
	v_max_u32_e32 v1, v32, v29
	v_min_u32_e32 v2, v32, v29
	v_max_u32_e32 v32, v28, v30
	v_min_u32_e32 v33, v28, v30
	v_max_u32_e32 v28, v31, v1
	v_min_u32_e32 v29, v31, v1
	v_max_u32_e32 v30, v32, v2
	v_min_u32_e32 v31, v32, v2
	v_max_u32_e32 v32, v33, v0
	v_min_u32_e32 v33, v33, v0
	v_max_u32_e32 v0, v52, v51
	v_min_u32_e32 v1, v52, v51
	v_max_u32_e32 v2, v50, v37
	v_min_u32_e32 v34, v50, v37
	v_min_u32_e32 v36, v41, v45
	v_max_u32_e32 v37, v49, v3
	v_min_u32_e32 v3, v49, v3
	v_max_u32_e32 v38, v0, v2
	v_min_u32_e32 v0, v0, v2
	v_max_u32_e32 v2, v1, v34
	v_min_u32_e32 v1, v1, v34
	v_max_u32_e32 v39, v35, v37
	v_min_u32_e32 v34, v35, v37
	v_max_u32_e32 v35, v36, v3
	v_min_u32_e32 v3, v36, v3
	v_max_u32_e32 v36, v2, v0
	v_min_u32_e32 v0, v2, v0
	v_max_u32_e32 v2, v35, v34
	v_min_u32_e32 v35, v35, v34
	v_max_u32_e32 v34, v38, v39
	v_min_u32_e32 v37, v38, v39
	v_max_u32_e32 v38, v36, v2
	v_min_u32_e32 v2, v36, v2
	v_max_u32_e32 v36, v0, v35
	v_max_u32_e32 v39, v1, v3
	v_min_u32_e32 v0, v0, v35
	v_min_u32_e32 v35, v1, v3
	v_max_u32_e32 v1, v36, v37
	v_min_u32_e32 v3, v36, v37
	v_max_u32_e32 v40, v39, v2
	v_min_u32_e32 v2, v39, v2
	v_max_u32_e32 v36, v38, v1
	v_min_u32_e32 v37, v38, v1
	v_max_u32_e32 v38, v40, v3
	v_min_u32_e32 v39, v40, v3
	v_max_u32_e32 v40, v2, v0
	v_min_u32_e32 v41, v2, v0
	v_mov_b32_e32 v0, 0
	v_mov_b32_e32 v1, 0
	v_mov_b32_e32 v2, 0
	v_mov_b32_e32 v3, 0
	v_pk_mov_b32 v[72:73], v[12:13], v[14:15] op_sel:[0,0] op_sel_hi:[0,0]
	v_pk_mov_b32 v[74:75], v[14:15], v[22:23] op_sel:[1,0] op_sel_hi:[1,0]
	v_pk_mov_b32 v[76:77], v[22:23], v[24:25] op_sel:[1,0] op_sel_hi:[1,0]
	v_pk_mov_b32 v[78:79], v[24:25], v[12:13] op_sel:[1,1] op_sel_hi:[1,1]
	v_pk_mov_b32 v[80:81], v[4:5], v[6:7] op_sel:[0,0] op_sel_hi:[0,0]
	v_pk_mov_b32 v[82:83], v[6:7], v[8:9] op_sel:[1,0] op_sel_hi:[1,0]
	v_pk_mov_b32 v[84:85], v[8:9], v[10:11] op_sel:[1,0] op_sel_hi:[1,0]
	v_pk_mov_b32 v[86:87], v[10:11], v[4:5] op_sel:[1,1] op_sel_hi:[1,1]
	v_pk_mov_b32 v[88:89], v[26:27], v[28:29] op_sel:[0,0] op_sel_hi:[0,0]
	v_pk_mov_b32 v[90:91], v[28:29], v[30:31] op_sel:[1,0] op_sel_hi:[1,0]
	v_pk_mov_b32 v[92:93], v[30:31], v[32:33] op_sel:[1,0] op_sel_hi:[1,0]
	v_pk_mov_b32 v[94:95], v[32:33], v[26:27] op_sel:[1,1] op_sel_hi:[1,1]
	v_pk_mov_b32 v[96:97], v[34:35], v[36:37] op_sel:[0,0] op_sel_hi:[0,0]
	v_pk_mov_b32 v[98:99], v[36:37], v[38:39] op_sel:[1,0] op_sel_hi:[1,0]
	v_pk_mov_b32 v[100:101], v[38:39], v[40:41] op_sel:[1,0] op_sel_hi:[1,0]
	v_pk_mov_b32 v[102:103], v[40:41], v[34:35] op_sel:[1,1] op_sel_hi:[1,1]
.LBB0_1349:
	v_max_u32_dpp v43, v72, v72 row_ror:1 row_mask:0xf bank_mask:0xf bound_ctrl:1
	v_max_u32_dpp v42, v80, v80 row_ror:1 row_mask:0xf bank_mask:0xf bound_ctrl:1
	v_max_u32_dpp v44, v88, v88 row_ror:1 row_mask:0xf bank_mask:0xf bound_ctrl:1
	v_max_u32_dpp v43, v43, v43 row_ror:2 row_mask:0xf bank_mask:0xf bound_ctrl:1
	v_max_u32_dpp v45, v96, v96 row_ror:1 row_mask:0xf bank_mask:0xf bound_ctrl:1
	v_max_u32_dpp v42, v42, v42 row_ror:2 row_mask:0xf bank_mask:0xf bound_ctrl:1
	v_max_u32_dpp v44, v44, v44 row_ror:2 row_mask:0xf bank_mask:0xf bound_ctrl:1
	v_max_u32_dpp v43, v43, v43 row_ror:4 row_mask:0xf bank_mask:0xf bound_ctrl:1
	v_max_u32_dpp v45, v45, v45 row_ror:2 row_mask:0xf bank_mask:0xf bound_ctrl:1
	v_max_u32_dpp v42, v42, v42 row_ror:4 row_mask:0xf bank_mask:0xf bound_ctrl:1
	v_max_u32_dpp v44, v44, v44 row_ror:4 row_mask:0xf bank_mask:0xf bound_ctrl:1
	v_max_u32_dpp v43, v43, v43 row_ror:8 row_mask:0xf bank_mask:0xf bound_ctrl:1
	v_max_u32_dpp v45, v45, v45 row_ror:4 row_mask:0xf bank_mask:0xf bound_ctrl:1
	v_max_u32_dpp v42, v42, v42 row_ror:8 row_mask:0xf bank_mask:0xf bound_ctrl:1
	v_max_u32_dpp v44, v44, v44 row_ror:8 row_mask:0xf bank_mask:0xf bound_ctrl:1
	v_max_u32_dpp v45, v45, v45 row_ror:8 row_mask:0xf bank_mask:0xf bound_ctrl:1
	v_cmp_eq_u32_e64 s[84:85], v72, v43
	v_cmp_eq_u32_e64 s[86:87], v80, v42
	v_cmp_eq_u32_e64 s[88:89], v88, v44
	v_cmp_eq_u32_e64 s[90:91], v96, v45
	s_mov_b64 exec, s[84:85]
	v_pk_mov_b32 v[72:73], v[72:73], v[74:75] op_sel:[1,0] op_sel_hi:[1,0]
	v_pk_mov_b32 v[74:75], v[74:75], v[76:77] op_sel:[1,0] op_sel_hi:[1,0]
	v_pk_mov_b32 v[76:77], v[76:77], v[78:79] op_sel:[1,0] op_sel_hi:[1,0]
	v_pk_mov_b32 v[78:79], v[78:79], v[70:71] op_sel:[1,0] op_sel_hi:[1,0]
	s_mov_b64 exec, s[86:87]
	v_pk_mov_b32 v[80:81], v[80:81], v[82:83] op_sel:[1,0] op_sel_hi:[1,0]
	v_pk_mov_b32 v[82:83], v[82:83], v[84:85] op_sel:[1,0] op_sel_hi:[1,0]
	v_pk_mov_b32 v[84:85], v[84:85], v[86:87] op_sel:[1,0] op_sel_hi:[1,0]
	v_pk_mov_b32 v[86:87], v[86:87], v[70:71] op_sel:[1,0] op_sel_hi:[1,0]
	s_mov_b64 exec, s[88:89]
	v_pk_mov_b32 v[88:89], v[88:89], v[90:91] op_sel:[1,0] op_sel_hi:[1,0]
	v_pk_mov_b32 v[90:91], v[90:91], v[92:93] op_sel:[1,0] op_sel_hi:[1,0]
	v_pk_mov_b32 v[92:93], v[92:93], v[94:95] op_sel:[1,0] op_sel_hi:[1,0]
	v_pk_mov_b32 v[94:95], v[94:95], v[70:71] op_sel:[1,0] op_sel_hi:[1,0]
	s_mov_b64 exec, s[90:91]
	v_pk_mov_b32 v[96:97], v[96:97], v[98:99] op_sel:[1,0] op_sel_hi:[1,0]
	v_pk_mov_b32 v[98:99], v[98:99], v[100:101] op_sel:[1,0] op_sel_hi:[1,0]
	v_pk_mov_b32 v[100:101], v[100:101], v[102:103] op_sel:[1,0] op_sel_hi:[1,0]
	v_pk_mov_b32 v[102:103], v[102:103], v[70:71] op_sel:[1,0] op_sel_hi:[1,0]
	s_lshl_b64 exec, s[78:79], s40
	s_add_i32 s40, s40, 1
	v_pk_mov_b32 v[0:1], v[42:43], v[42:43] op_sel:[0,1] op_sel_hi:[0,1]
	v_pk_mov_b32 v[2:3], v[44:45], v[44:45] op_sel:[0,1] op_sel_hi:[0,1]
	s_mov_b64 exec, -1
	s_cmp_lg_u32 s40, 8
	s_cbranch_scc1 .LBB0_1349
	v_max_u32_dpp v43, v72, v72 row_ror:1 row_mask:0xf bank_mask:0xf bound_ctrl:1
	v_max_u32_dpp v42, v80, v80 row_ror:1 row_mask:0xf bank_mask:0xf bound_ctrl:1
	v_max_u32_dpp v44, v88, v88 row_ror:1 row_mask:0xf bank_mask:0xf bound_ctrl:1
	v_max_u32_dpp v43, v43, v43 row_ror:2 row_mask:0xf bank_mask:0xf bound_ctrl:1
	v_max_u32_dpp v45, v96, v96 row_ror:1 row_mask:0xf bank_mask:0xf bound_ctrl:1
	v_max_u32_dpp v42, v42, v42 row_ror:2 row_mask:0xf bank_mask:0xf bound_ctrl:1
	v_max_u32_dpp v44, v44, v44 row_ror:2 row_mask:0xf bank_mask:0xf bound_ctrl:1
	v_max_u32_dpp v43, v43, v43 row_ror:4 row_mask:0xf bank_mask:0xf bound_ctrl:1
	v_max_u32_dpp v45, v45, v45 row_ror:2 row_mask:0xf bank_mask:0xf bound_ctrl:1
	v_max_u32_dpp v42, v42, v42 row_ror:4 row_mask:0xf bank_mask:0xf bound_ctrl:1
	v_max_u32_dpp v44, v44, v44 row_ror:4 row_mask:0xf bank_mask:0xf bound_ctrl:1
	v_max_u32_dpp v43, v43, v43 row_ror:8 row_mask:0xf bank_mask:0xf bound_ctrl:1
	v_max_u32_dpp v45, v45, v45 row_ror:4 row_mask:0xf bank_mask:0xf bound_ctrl:1
	v_max_u32_dpp v42, v42, v42 row_ror:8 row_mask:0xf bank_mask:0xf bound_ctrl:1
	v_max_u32_dpp v44, v44, v44 row_ror:8 row_mask:0xf bank_mask:0xf bound_ctrl:1
	v_max_u32_dpp v45, v45, v45 row_ror:8 row_mask:0xf bank_mask:0xf bound_ctrl:1
	v_cmp_eq_u32_e64 s[84:85], v72, v43
	v_cmp_eq_u32_e64 s[86:87], v80, v42
	v_cmp_eq_u32_e64 s[88:89], v88, v44
	v_cmp_eq_u32_e64 s[90:91], v96, v45
	s_mov_b64 exec, s[84:85]
	v_pk_mov_b32 v[72:73], v[72:73], v[74:75] op_sel:[1,0] op_sel_hi:[1,0]
	v_pk_mov_b32 v[74:75], v[74:75], v[76:77] op_sel:[1,0] op_sel_hi:[1,0]
	v_pk_mov_b32 v[76:77], v[76:77], v[78:79] op_sel:[1,0] op_sel_hi:[1,0]
	v_pk_mov_b32 v[78:79], v[78:79], v[70:71] op_sel:[1,0] op_sel_hi:[1,0]
	s_mov_b64 exec, s[86:87]
	v_pk_mov_b32 v[80:81], v[80:81], v[82:83] op_sel:[1,0] op_sel_hi:[1,0]
	v_pk_mov_b32 v[82:83], v[82:83], v[84:85] op_sel:[1,0] op_sel_hi:[1,0]
	v_pk_mov_b32 v[84:85], v[84:85], v[86:87] op_sel:[1,0] op_sel_hi:[1,0]
	v_pk_mov_b32 v[86:87], v[86:87], v[70:71] op_sel:[1,0] op_sel_hi:[1,0]
	s_mov_b64 exec, s[88:89]
	v_pk_mov_b32 v[88:89], v[88:89], v[90:91] op_sel:[1,0] op_sel_hi:[1,0]
	v_pk_mov_b32 v[90:91], v[90:91], v[92:93] op_sel:[1,0] op_sel_hi:[1,0]
	v_pk_mov_b32 v[92:93], v[92:93], v[94:95] op_sel:[1,0] op_sel_hi:[1,0]
	v_pk_mov_b32 v[94:95], v[94:95], v[70:71] op_sel:[1,0] op_sel_hi:[1,0]
	s_mov_b64 exec, s[90:91]
	v_pk_mov_b32 v[96:97], v[96:97], v[98:99] op_sel:[1,0] op_sel_hi:[1,0]
	v_pk_mov_b32 v[98:99], v[98:99], v[100:101] op_sel:[1,0] op_sel_hi:[1,0]
	v_pk_mov_b32 v[100:101], v[100:101], v[102:103] op_sel:[1,0] op_sel_hi:[1,0]
	v_pk_mov_b32 v[102:103], v[102:103], v[70:71] op_sel:[1,0] op_sel_hi:[1,0]
	s_lshl_b64 exec, s[78:79], s40
	s_add_i32 s40, s40, 1
	v_pk_mov_b32 v[0:1], v[42:43], v[42:43] op_sel:[0,1] op_sel_hi:[0,1]
	v_pk_mov_b32 v[2:3], v[44:45], v[44:45] op_sel:[0,1] op_sel_hi:[0,1]
	s_mov_b64 exec, -1
	v_max_u32_dpp v43, v72, v72 row_ror:1 row_mask:0xf bank_mask:0xf bound_ctrl:1
	v_max_u32_dpp v42, v80, v80 row_ror:1 row_mask:0xf bank_mask:0xf bound_ctrl:1
	v_max_u32_dpp v44, v88, v88 row_ror:1 row_mask:0xf bank_mask:0xf bound_ctrl:1
	v_max_u32_dpp v43, v43, v43 row_ror:2 row_mask:0xf bank_mask:0xf bound_ctrl:1
	v_max_u32_dpp v45, v96, v96 row_ror:1 row_mask:0xf bank_mask:0xf bound_ctrl:1
	v_max_u32_dpp v42, v42, v42 row_ror:2 row_mask:0xf bank_mask:0xf bound_ctrl:1
	v_max_u32_dpp v44, v44, v44 row_ror:2 row_mask:0xf bank_mask:0xf bound_ctrl:1
	v_max_u32_dpp v43, v43, v43 row_ror:4 row_mask:0xf bank_mask:0xf bound_ctrl:1
	v_max_u32_dpp v45, v45, v45 row_ror:2 row_mask:0xf bank_mask:0xf bound_ctrl:1
	v_max_u32_dpp v42, v42, v42 row_ror:4 row_mask:0xf bank_mask:0xf bound_ctrl:1
	v_max_u32_dpp v44, v44, v44 row_ror:4 row_mask:0xf bank_mask:0xf bound_ctrl:1
	v_max_u32_dpp v43, v43, v43 row_ror:8 row_mask:0xf bank_mask:0xf bound_ctrl:1
	v_max_u32_dpp v45, v45, v45 row_ror:4 row_mask:0xf bank_mask:0xf bound_ctrl:1
	v_max_u32_dpp v42, v42, v42 row_ror:8 row_mask:0xf bank_mask:0xf bound_ctrl:1
	v_max_u32_dpp v44, v44, v44 row_ror:8 row_mask:0xf bank_mask:0xf bound_ctrl:1
	v_max_u32_dpp v45, v45, v45 row_ror:8 row_mask:0xf bank_mask:0xf bound_ctrl:1
	v_cmp_eq_u32_e64 s[84:85], v72, v43
	v_cmp_eq_u32_e64 s[86:87], v80, v42
	v_cmp_eq_u32_e64 s[88:89], v88, v44
	v_cmp_eq_u32_e64 s[90:91], v96, v45
	s_mov_b64 exec, s[84:85]
	v_pk_mov_b32 v[72:73], v[72:73], v[74:75] op_sel:[1,0] op_sel_hi:[1,0]
	v_pk_mov_b32 v[74:75], v[74:75], v[76:77] op_sel:[1,0] op_sel_hi:[1,0]
	v_pk_mov_b32 v[76:77], v[76:77], v[78:79] op_sel:[1,0] op_sel_hi:[1,0]
	s_mov_b64 exec, s[86:87]
	v_pk_mov_b32 v[80:81], v[80:81], v[82:83] op_sel:[1,0] op_sel_hi:[1,0]
	v_pk_mov_b32 v[82:83], v[82:83], v[84:85] op_sel:[1,0] op_sel_hi:[1,0]
	v_pk_mov_b32 v[84:85], v[84:85], v[86:87] op_sel:[1,0] op_sel_hi:[1,0]
	s_mov_b64 exec, s[88:89]
	v_pk_mov_b32 v[88:89], v[88:89], v[90:91] op_sel:[1,0] op_sel_hi:[1,0]
	v_pk_mov_b32 v[90:91], v[90:91], v[92:93] op_sel:[1,0] op_sel_hi:[1,0]
	v_pk_mov_b32 v[92:93], v[92:93], v[94:95] op_sel:[1,0] op_sel_hi:[1,0]
	s_mov_b64 exec, s[90:91]
	v_pk_mov_b32 v[96:97], v[96:97], v[98:99] op_sel:[1,0] op_sel_hi:[1,0]
	v_pk_mov_b32 v[98:99], v[98:99], v[100:101] op_sel:[1,0] op_sel_hi:[1,0]
	v_pk_mov_b32 v[100:101], v[100:101], v[102:103] op_sel:[1,0] op_sel_hi:[1,0]
	s_lshl_b64 exec, s[78:79], s40
	s_add_i32 s40, s40, 1
	v_pk_mov_b32 v[0:1], v[42:43], v[42:43] op_sel:[0,1] op_sel_hi:[0,1]
	v_pk_mov_b32 v[2:3], v[44:45], v[44:45] op_sel:[0,1] op_sel_hi:[0,1]
	s_mov_b64 exec, -1
	v_max_u32_dpp v43, v72, v72 row_ror:1 row_mask:0xf bank_mask:0xf bound_ctrl:1
	v_max_u32_dpp v42, v80, v80 row_ror:1 row_mask:0xf bank_mask:0xf bound_ctrl:1
	v_max_u32_dpp v44, v88, v88 row_ror:1 row_mask:0xf bank_mask:0xf bound_ctrl:1
	v_max_u32_dpp v43, v43, v43 row_ror:2 row_mask:0xf bank_mask:0xf bound_ctrl:1
	v_max_u32_dpp v45, v96, v96 row_ror:1 row_mask:0xf bank_mask:0xf bound_ctrl:1
	v_max_u32_dpp v42, v42, v42 row_ror:2 row_mask:0xf bank_mask:0xf bound_ctrl:1
	v_max_u32_dpp v44, v44, v44 row_ror:2 row_mask:0xf bank_mask:0xf bound_ctrl:1
	v_max_u32_dpp v43, v43, v43 row_ror:4 row_mask:0xf bank_mask:0xf bound_ctrl:1
	v_max_u32_dpp v45, v45, v45 row_ror:2 row_mask:0xf bank_mask:0xf bound_ctrl:1
	v_max_u32_dpp v42, v42, v42 row_ror:4 row_mask:0xf bank_mask:0xf bound_ctrl:1
	v_max_u32_dpp v44, v44, v44 row_ror:4 row_mask:0xf bank_mask:0xf bound_ctrl:1
	v_max_u32_dpp v43, v43, v43 row_ror:8 row_mask:0xf bank_mask:0xf bound_ctrl:1
	v_max_u32_dpp v45, v45, v45 row_ror:4 row_mask:0xf bank_mask:0xf bound_ctrl:1
	v_max_u32_dpp v42, v42, v42 row_ror:8 row_mask:0xf bank_mask:0xf bound_ctrl:1
	v_max_u32_dpp v44, v44, v44 row_ror:8 row_mask:0xf bank_mask:0xf bound_ctrl:1
	v_max_u32_dpp v45, v45, v45 row_ror:8 row_mask:0xf bank_mask:0xf bound_ctrl:1
	v_cmp_eq_u32_e64 s[84:85], v72, v43
	v_cmp_eq_u32_e64 s[86:87], v80, v42
	v_cmp_eq_u32_e64 s[88:89], v88, v44
	v_cmp_eq_u32_e64 s[90:91], v96, v45
	s_mov_b64 exec, s[84:85]
	v_pk_mov_b32 v[72:73], v[72:73], v[74:75] op_sel:[1,0] op_sel_hi:[1,0]
	v_pk_mov_b32 v[74:75], v[74:75], v[76:77] op_sel:[1,0] op_sel_hi:[1,0]
	v_pk_mov_b32 v[76:77], v[76:77], v[78:79] op_sel:[1,0] op_sel_hi:[1,0]
	s_mov_b64 exec, s[86:87]
	v_pk_mov_b32 v[80:81], v[80:81], v[82:83] op_sel:[1,0] op_sel_hi:[1,0]
	v_pk_mov_b32 v[82:83], v[82:83], v[84:85] op_sel:[1,0] op_sel_hi:[1,0]
	v_pk_mov_b32 v[84:85], v[84:85], v[86:87] op_sel:[1,0] op_sel_hi:[1,0]
	s_mov_b64 exec, s[88:89]
	v_pk_mov_b32 v[88:89], v[88:89], v[90:91] op_sel:[1,0] op_sel_hi:[1,0]
	v_pk_mov_b32 v[90:91], v[90:91], v[92:93] op_sel:[1,0] op_sel_hi:[1,0]
	v_pk_mov_b32 v[92:93], v[92:93], v[94:95] op_sel:[1,0] op_sel_hi:[1,0]
	s_mov_b64 exec, s[90:91]
	v_pk_mov_b32 v[96:97], v[96:97], v[98:99] op_sel:[1,0] op_sel_hi:[1,0]
	v_pk_mov_b32 v[98:99], v[98:99], v[100:101] op_sel:[1,0] op_sel_hi:[1,0]
	v_pk_mov_b32 v[100:101], v[100:101], v[102:103] op_sel:[1,0] op_sel_hi:[1,0]
	s_lshl_b64 exec, s[78:79], s40
	s_add_i32 s40, s40, 1
	v_pk_mov_b32 v[0:1], v[42:43], v[42:43] op_sel:[0,1] op_sel_hi:[0,1]
	v_pk_mov_b32 v[2:3], v[44:45], v[44:45] op_sel:[0,1] op_sel_hi:[0,1]
	s_mov_b64 exec, -1
	v_max_u32_dpp v43, v72, v72 row_ror:1 row_mask:0xf bank_mask:0xf bound_ctrl:1
	v_max_u32_dpp v42, v80, v80 row_ror:1 row_mask:0xf bank_mask:0xf bound_ctrl:1
	v_max_u32_dpp v44, v88, v88 row_ror:1 row_mask:0xf bank_mask:0xf bound_ctrl:1
	v_max_u32_dpp v43, v43, v43 row_ror:2 row_mask:0xf bank_mask:0xf bound_ctrl:1
	v_max_u32_dpp v45, v96, v96 row_ror:1 row_mask:0xf bank_mask:0xf bound_ctrl:1
	v_max_u32_dpp v42, v42, v42 row_ror:2 row_mask:0xf bank_mask:0xf bound_ctrl:1
	v_max_u32_dpp v44, v44, v44 row_ror:2 row_mask:0xf bank_mask:0xf bound_ctrl:1
	v_max_u32_dpp v43, v43, v43 row_ror:4 row_mask:0xf bank_mask:0xf bound_ctrl:1
	v_max_u32_dpp v45, v45, v45 row_ror:2 row_mask:0xf bank_mask:0xf bound_ctrl:1
	v_max_u32_dpp v42, v42, v42 row_ror:4 row_mask:0xf bank_mask:0xf bound_ctrl:1
	v_max_u32_dpp v44, v44, v44 row_ror:4 row_mask:0xf bank_mask:0xf bound_ctrl:1
	v_max_u32_dpp v43, v43, v43 row_ror:8 row_mask:0xf bank_mask:0xf bound_ctrl:1
	v_max_u32_dpp v45, v45, v45 row_ror:4 row_mask:0xf bank_mask:0xf bound_ctrl:1
	v_max_u32_dpp v42, v42, v42 row_ror:8 row_mask:0xf bank_mask:0xf bound_ctrl:1
	v_max_u32_dpp v44, v44, v44 row_ror:8 row_mask:0xf bank_mask:0xf bound_ctrl:1
	v_max_u32_dpp v45, v45, v45 row_ror:8 row_mask:0xf bank_mask:0xf bound_ctrl:1
	v_cmp_eq_u32_e64 s[84:85], v72, v43
	v_cmp_eq_u32_e64 s[86:87], v80, v42
	v_cmp_eq_u32_e64 s[88:89], v88, v44
	v_cmp_eq_u32_e64 s[90:91], v96, v45
	s_mov_b64 exec, s[84:85]
	v_pk_mov_b32 v[72:73], v[72:73], v[74:75] op_sel:[1,0] op_sel_hi:[1,0]
	v_pk_mov_b32 v[74:75], v[74:75], v[76:77] op_sel:[1,0] op_sel_hi:[1,0]
	s_mov_b64 exec, s[86:87]
	v_pk_mov_b32 v[80:81], v[80:81], v[82:83] op_sel:[1,0] op_sel_hi:[1,0]
	v_pk_mov_b32 v[82:83], v[82:83], v[84:85] op_sel:[1,0] op_sel_hi:[1,0]
	s_mov_b64 exec, s[88:89]
	v_pk_mov_b32 v[88:89], v[88:89], v[90:91] op_sel:[1,0] op_sel_hi:[1,0]
	v_pk_mov_b32 v[90:91], v[90:91], v[92:93] op_sel:[1,0] op_sel_hi:[1,0]
	s_mov_b64 exec, s[90:91]
	v_pk_mov_b32 v[96:97], v[96:97], v[98:99] op_sel:[1,0] op_sel_hi:[1,0]
	v_pk_mov_b32 v[98:99], v[98:99], v[100:101] op_sel:[1,0] op_sel_hi:[1,0]
	s_lshl_b64 exec, s[78:79], s40
	s_add_i32 s40, s40, 1
	v_pk_mov_b32 v[0:1], v[42:43], v[42:43] op_sel:[0,1] op_sel_hi:[0,1]
	v_pk_mov_b32 v[2:3], v[44:45], v[44:45] op_sel:[0,1] op_sel_hi:[0,1]
	s_mov_b64 exec, -1
	v_max_u32_dpp v43, v72, v72 row_ror:1 row_mask:0xf bank_mask:0xf bound_ctrl:1
	v_max_u32_dpp v42, v80, v80 row_ror:1 row_mask:0xf bank_mask:0xf bound_ctrl:1
	v_max_u32_dpp v44, v88, v88 row_ror:1 row_mask:0xf bank_mask:0xf bound_ctrl:1
	v_max_u32_dpp v43, v43, v43 row_ror:2 row_mask:0xf bank_mask:0xf bound_ctrl:1
	v_max_u32_dpp v45, v96, v96 row_ror:1 row_mask:0xf bank_mask:0xf bound_ctrl:1
	v_max_u32_dpp v42, v42, v42 row_ror:2 row_mask:0xf bank_mask:0xf bound_ctrl:1
	v_max_u32_dpp v44, v44, v44 row_ror:2 row_mask:0xf bank_mask:0xf bound_ctrl:1
	v_max_u32_dpp v43, v43, v43 row_ror:4 row_mask:0xf bank_mask:0xf bound_ctrl:1
	v_max_u32_dpp v45, v45, v45 row_ror:2 row_mask:0xf bank_mask:0xf bound_ctrl:1
	v_max_u32_dpp v42, v42, v42 row_ror:4 row_mask:0xf bank_mask:0xf bound_ctrl:1
	v_max_u32_dpp v44, v44, v44 row_ror:4 row_mask:0xf bank_mask:0xf bound_ctrl:1
	v_max_u32_dpp v43, v43, v43 row_ror:8 row_mask:0xf bank_mask:0xf bound_ctrl:1
	v_max_u32_dpp v45, v45, v45 row_ror:4 row_mask:0xf bank_mask:0xf bound_ctrl:1
	v_max_u32_dpp v42, v42, v42 row_ror:8 row_mask:0xf bank_mask:0xf bound_ctrl:1
	v_max_u32_dpp v44, v44, v44 row_ror:8 row_mask:0xf bank_mask:0xf bound_ctrl:1
	v_max_u32_dpp v45, v45, v45 row_ror:8 row_mask:0xf bank_mask:0xf bound_ctrl:1
	v_cmp_eq_u32_e64 s[84:85], v72, v43
	v_cmp_eq_u32_e64 s[86:87], v80, v42
	v_cmp_eq_u32_e64 s[88:89], v88, v44
	v_cmp_eq_u32_e64 s[90:91], v96, v45
	s_mov_b64 exec, s[84:85]
	v_pk_mov_b32 v[72:73], v[72:73], v[74:75] op_sel:[1,0] op_sel_hi:[1,0]
	v_pk_mov_b32 v[74:75], v[74:75], v[76:77] op_sel:[1,0] op_sel_hi:[1,0]
	s_mov_b64 exec, s[86:87]
	v_pk_mov_b32 v[80:81], v[80:81], v[82:83] op_sel:[1,0] op_sel_hi:[1,0]
	v_pk_mov_b32 v[82:83], v[82:83], v[84:85] op_sel:[1,0] op_sel_hi:[1,0]
	s_mov_b64 exec, s[88:89]
	v_pk_mov_b32 v[88:89], v[88:89], v[90:91] op_sel:[1,0] op_sel_hi:[1,0]
	v_pk_mov_b32 v[90:91], v[90:91], v[92:93] op_sel:[1,0] op_sel_hi:[1,0]
	s_mov_b64 exec, s[90:91]
	v_pk_mov_b32 v[96:97], v[96:97], v[98:99] op_sel:[1,0] op_sel_hi:[1,0]
	v_pk_mov_b32 v[98:99], v[98:99], v[100:101] op_sel:[1,0] op_sel_hi:[1,0]
	s_lshl_b64 exec, s[78:79], s40
	s_add_i32 s40, s40, 1
	v_pk_mov_b32 v[0:1], v[42:43], v[42:43] op_sel:[0,1] op_sel_hi:[0,1]
	v_pk_mov_b32 v[2:3], v[44:45], v[44:45] op_sel:[0,1] op_sel_hi:[0,1]
	s_mov_b64 exec, -1
	v_max_u32_dpp v43, v72, v72 row_ror:1 row_mask:0xf bank_mask:0xf bound_ctrl:1
	v_max_u32_dpp v42, v80, v80 row_ror:1 row_mask:0xf bank_mask:0xf bound_ctrl:1
	v_max_u32_dpp v44, v88, v88 row_ror:1 row_mask:0xf bank_mask:0xf bound_ctrl:1
	v_max_u32_dpp v43, v43, v43 row_ror:2 row_mask:0xf bank_mask:0xf bound_ctrl:1
	v_max_u32_dpp v45, v96, v96 row_ror:1 row_mask:0xf bank_mask:0xf bound_ctrl:1
	v_max_u32_dpp v42, v42, v42 row_ror:2 row_mask:0xf bank_mask:0xf bound_ctrl:1
	v_max_u32_dpp v44, v44, v44 row_ror:2 row_mask:0xf bank_mask:0xf bound_ctrl:1
	v_max_u32_dpp v43, v43, v43 row_ror:4 row_mask:0xf bank_mask:0xf bound_ctrl:1
	v_max_u32_dpp v45, v45, v45 row_ror:2 row_mask:0xf bank_mask:0xf bound_ctrl:1
	v_max_u32_dpp v42, v42, v42 row_ror:4 row_mask:0xf bank_mask:0xf bound_ctrl:1
	v_max_u32_dpp v44, v44, v44 row_ror:4 row_mask:0xf bank_mask:0xf bound_ctrl:1
	v_max_u32_dpp v43, v43, v43 row_ror:8 row_mask:0xf bank_mask:0xf bound_ctrl:1
	v_max_u32_dpp v45, v45, v45 row_ror:4 row_mask:0xf bank_mask:0xf bound_ctrl:1
	v_max_u32_dpp v42, v42, v42 row_ror:8 row_mask:0xf bank_mask:0xf bound_ctrl:1
	v_max_u32_dpp v44, v44, v44 row_ror:8 row_mask:0xf bank_mask:0xf bound_ctrl:1
	v_max_u32_dpp v45, v45, v45 row_ror:8 row_mask:0xf bank_mask:0xf bound_ctrl:1
	v_cmp_eq_u32_e64 s[84:85], v72, v43
	v_cmp_eq_u32_e64 s[86:87], v80, v42
	v_cmp_eq_u32_e64 s[88:89], v88, v44
	v_cmp_eq_u32_e64 s[90:91], v96, v45
	s_mov_b64 exec, s[84:85]
	v_pk_mov_b32 v[72:73], v[72:73], v[74:75] op_sel:[1,0] op_sel_hi:[1,0]
	s_mov_b64 exec, s[86:87]
	v_pk_mov_b32 v[80:81], v[80:81], v[82:83] op_sel:[1,0] op_sel_hi:[1,0]
	s_mov_b64 exec, s[88:89]
	v_pk_mov_b32 v[88:89], v[88:89], v[90:91] op_sel:[1,0] op_sel_hi:[1,0]
	s_mov_b64 exec, s[90:91]
	v_pk_mov_b32 v[96:97], v[96:97], v[98:99] op_sel:[1,0] op_sel_hi:[1,0]
	s_lshl_b64 exec, s[78:79], s40
	s_add_i32 s40, s40, 1
	v_pk_mov_b32 v[0:1], v[42:43], v[42:43] op_sel:[0,1] op_sel_hi:[0,1]
	v_pk_mov_b32 v[2:3], v[44:45], v[44:45] op_sel:[0,1] op_sel_hi:[0,1]
	s_mov_b64 exec, -1
	v_max_u32_dpp v43, v72, v72 row_ror:1 row_mask:0xf bank_mask:0xf bound_ctrl:1
	v_max_u32_dpp v42, v80, v80 row_ror:1 row_mask:0xf bank_mask:0xf bound_ctrl:1
	v_max_u32_dpp v44, v88, v88 row_ror:1 row_mask:0xf bank_mask:0xf bound_ctrl:1
	v_max_u32_dpp v43, v43, v43 row_ror:2 row_mask:0xf bank_mask:0xf bound_ctrl:1
	v_max_u32_dpp v45, v96, v96 row_ror:1 row_mask:0xf bank_mask:0xf bound_ctrl:1
	v_max_u32_dpp v42, v42, v42 row_ror:2 row_mask:0xf bank_mask:0xf bound_ctrl:1
	v_max_u32_dpp v44, v44, v44 row_ror:2 row_mask:0xf bank_mask:0xf bound_ctrl:1
	v_max_u32_dpp v43, v43, v43 row_ror:4 row_mask:0xf bank_mask:0xf bound_ctrl:1
	v_max_u32_dpp v45, v45, v45 row_ror:2 row_mask:0xf bank_mask:0xf bound_ctrl:1
	v_max_u32_dpp v42, v42, v42 row_ror:4 row_mask:0xf bank_mask:0xf bound_ctrl:1
	v_max_u32_dpp v44, v44, v44 row_ror:4 row_mask:0xf bank_mask:0xf bound_ctrl:1
	v_max_u32_dpp v43, v43, v43 row_ror:8 row_mask:0xf bank_mask:0xf bound_ctrl:1
	v_max_u32_dpp v45, v45, v45 row_ror:4 row_mask:0xf bank_mask:0xf bound_ctrl:1
	v_max_u32_dpp v42, v42, v42 row_ror:8 row_mask:0xf bank_mask:0xf bound_ctrl:1
	v_max_u32_dpp v44, v44, v44 row_ror:8 row_mask:0xf bank_mask:0xf bound_ctrl:1
	v_max_u32_dpp v45, v45, v45 row_ror:8 row_mask:0xf bank_mask:0xf bound_ctrl:1
	v_cmp_eq_u32_e64 s[84:85], v72, v43
	v_cmp_eq_u32_e64 s[86:87], v80, v42
	v_cmp_eq_u32_e64 s[88:89], v88, v44
	v_cmp_eq_u32_e64 s[90:91], v96, v45
	s_mov_b64 exec, s[84:85]
	v_pk_mov_b32 v[72:73], v[72:73], v[74:75] op_sel:[1,0] op_sel_hi:[1,0]
	s_mov_b64 exec, s[86:87]
	v_pk_mov_b32 v[80:81], v[80:81], v[82:83] op_sel:[1,0] op_sel_hi:[1,0]
	s_mov_b64 exec, s[88:89]
	v_pk_mov_b32 v[88:89], v[88:89], v[90:91] op_sel:[1,0] op_sel_hi:[1,0]
	s_mov_b64 exec, s[90:91]
	v_pk_mov_b32 v[96:97], v[96:97], v[98:99] op_sel:[1,0] op_sel_hi:[1,0]
	s_lshl_b64 exec, s[78:79], s40
	s_add_i32 s40, s40, 1
	v_pk_mov_b32 v[0:1], v[42:43], v[42:43] op_sel:[0,1] op_sel_hi:[0,1]
	v_pk_mov_b32 v[2:3], v[44:45], v[44:45] op_sel:[0,1] op_sel_hi:[0,1]
	s_mov_b64 exec, -1
	v_max_u32_dpp v43, v72, v72 row_ror:1 row_mask:0xf bank_mask:0xf bound_ctrl:1
	v_max_u32_dpp v42, v80, v80 row_ror:1 row_mask:0xf bank_mask:0xf bound_ctrl:1
	v_max_u32_dpp v44, v88, v88 row_ror:1 row_mask:0xf bank_mask:0xf bound_ctrl:1
	v_max_u32_dpp v43, v43, v43 row_ror:2 row_mask:0xf bank_mask:0xf bound_ctrl:1
	v_max_u32_dpp v45, v96, v96 row_ror:1 row_mask:0xf bank_mask:0xf bound_ctrl:1
	v_max_u32_dpp v42, v42, v42 row_ror:2 row_mask:0xf bank_mask:0xf bound_ctrl:1
	v_max_u32_dpp v44, v44, v44 row_ror:2 row_mask:0xf bank_mask:0xf bound_ctrl:1
	v_max_u32_dpp v43, v43, v43 row_ror:4 row_mask:0xf bank_mask:0xf bound_ctrl:1
	v_max_u32_dpp v45, v45, v45 row_ror:2 row_mask:0xf bank_mask:0xf bound_ctrl:1
	v_max_u32_dpp v42, v42, v42 row_ror:4 row_mask:0xf bank_mask:0xf bound_ctrl:1
	v_max_u32_dpp v44, v44, v44 row_ror:4 row_mask:0xf bank_mask:0xf bound_ctrl:1
	v_max_u32_dpp v43, v43, v43 row_ror:8 row_mask:0xf bank_mask:0xf bound_ctrl:1
	v_max_u32_dpp v45, v45, v45 row_ror:4 row_mask:0xf bank_mask:0xf bound_ctrl:1
	v_max_u32_dpp v42, v42, v42 row_ror:8 row_mask:0xf bank_mask:0xf bound_ctrl:1
	v_max_u32_dpp v44, v44, v44 row_ror:8 row_mask:0xf bank_mask:0xf bound_ctrl:1
	v_max_u32_dpp v45, v45, v45 row_ror:8 row_mask:0xf bank_mask:0xf bound_ctrl:1
	s_lshl_b64 exec, s[78:79], s40
	v_pk_mov_b32 v[0:1], v[42:43], v[42:43] op_sel:[0,1] op_sel_hi:[0,1]
	v_pk_mov_b32 v[2:3], v[44:45], v[44:45] op_sel:[0,1] op_sel_hi:[0,1]
	s_mov_b64 exec, -1
	v_cmp_lt_i32_e32 vcc, -1, v18
	v_mov_b32_e32 v6, 0
	v_mov_b32_e32 v7, 0
	v_cndmask_b32_e64 v4, v217, -1, vcc
	v_cmp_lt_i32_e32 vcc, -1, v0
	v_bitop3_b32 v8, v4, v18, s67 bitop3:0x78
	ds_bpermute_b32 v10, v198, v8
	v_cndmask_b32_e64 v4, v217, -1, vcc
	v_bitop3_b32 v9, v4, v0, s67 bitop3:0x78
	ds_bpermute_b32 v4, v196, v8
	ds_bpermute_b32 v5, v197, v9
	ds_bpermute_b32 v11, v199, v9
	s_and_saveexec_b64 s[0:1], s[6:7]
	s_cbranch_execz .LBB0_1352
	s_waitcnt lgkmcnt(0)
	v_add_f32_e32 v7, v10, v11
	v_cmp_lt_i32_e32 vcc, -1, v7
	s_nop 1
	v_cndmask_b32_e32 v10, -1, v217, vcc
	v_bitop3_b32 v7, v10, s59, v7 bitop3:0x48
	v_bitop3_b32 v7, v7, s54, v172 bitop3:0x36

.LBB0_1374:
	s_or_b64 exec, exec, s[0:1]
	v_add_f32_e32 v25, v25, v29
	v_cmp_lt_i32_e32 vcc, -1, v25
	v_add_f32_e32 v22, v22, v23
	v_add_f32_e32 v10, v10, v11
	v_cndmask_b32_e32 v29, -1, v217, vcc
	v_cmp_lt_i32_e32 vcc, -1, v22
	v_add_f32_e32 v4, v4, v5
	v_bitop3_b32 v25, v29, s59, v25 bitop3:0x48
	v_cndmask_b32_e32 v23, -1, v217, vcc
	v_cmp_lt_i32_e32 vcc, -1, v10
	v_bitop3_b32 v22, v23, s59, v22 bitop3:0x48
	v_bitop3_b32 v29, v25, s54, v174 bitop3:0x36
	v_cndmask_b32_e32 v11, -1, v217, vcc
	v_cmp_lt_i32_e32 vcc, -1, v4
	v_bitop3_b32 v10, v11, s59, v10 bitop3:0x48
	v_bitop3_b32 v23, v10, s54, v174 bitop3:0x36
	v_cndmask_b32_e32 v5, -1, v217, vcc
	v_bitop3_b32 v4, v5, s59, v4 bitop3:0x48
	v_bitop3_b32 v4, v4, s54, v174 bitop3:0x36
	v_max_u32_e32 v5, v4, v7
	v_min_u32_e32 v4, v4, v7
	v_max_u32_e32 v7, v6, v9
	v_min_u32_e32 v6, v6, v9
	v_max_u32_e32 v9, v5, v7
	v_min_u32_e32 v5, v5, v7
	v_max_u32_e32 v7, v4, v6
	v_bitop3_b32 v25, v22, s54, v174 bitop3:0x36
	v_min_u32_e32 v10, v4, v6
	v_max_u32_e32 v11, v7, v5
	v_min_u32_e32 v22, v7, v5
	v_max_u32_e32 v4, v23, v8
	v_min_u32_e32 v5, v23, v8
	v_max_u32_e32 v6, v13, v12
	v_min_u32_e32 v7, v13, v12
	v_max_u32_e32 v8, v4, v6
	v_min_u32_e32 v4, v4, v6
	v_max_u32_e32 v6, v5, v7
	v_min_u32_e32 v12, v5, v7
	v_max_u32_e32 v13, v6, v4
	v_min_u32_e32 v23, v6, v4
	v_max_u32_e32 v4, v25, v15
	v_min_u32_e32 v5, v25, v15
	v_max_u32_e32 v6, v14, v24
	v_min_u32_e32 v7, v14, v24
	v_max_u32_e32 v14, v4, v6
	v_min_u32_e32 v4, v4, v6
	v_max_u32_e32 v6, v5, v7
	v_min_u32_e32 v15, v5, v7
	v_max_u32_e32 v24, v6, v4
	v_min_u32_e32 v25, v6, v4
	v_max_u32_e32 v4, v29, v26
	v_min_u32_e32 v5, v29, v26
	v_max_u32_e32 v6, v28, v27
	v_min_u32_e32 v7, v28, v27
	v_max_u32_e32 v26, v4, v6
	v_min_u32_e32 v4, v4, v6
	v_max_u32_e32 v6, v5, v7
	v_min_u32_e32 v27, v5, v7
	v_max_u32_e32 v28, v6, v4
	v_min_u32_e32 v29, v6, v4
	s_mov_b32 s40, 0
	v_mov_b32_e32 v7, 0
	v_mov_b32_e32 v6, 0
	v_mov_b32_e32 v5, 0
	v_mov_b32_e32 v4, 0
	v_pk_mov_b32 v[72:73], v[8:9], v[12:13] op_sel:[0,1] op_sel_hi:[0,1]
	v_pk_mov_b32 v[74:75], v[22:23], v[12:13] op_sel:[1,0] op_sel_hi:[1,0]
	v_pk_mov_b32 v[76:77], v[8:9], v[10:11] op_sel:[1,1] op_sel_hi:[1,1]
	v_pk_mov_b32 v[78:79], v[22:23], v[10:11] op_sel:[0,0] op_sel_hi:[0,0]
	v_pk_mov_b32 v[80:81], v[14:15], v[24:25] op_sel:[0,0] op_sel_hi:[0,0]
	v_pk_mov_b32 v[82:83], v[24:25], v[14:15] op_sel:[1,1] op_sel_hi:[1,1]
	v_pk_mov_b32 v[84:85], v[26:27], v[28:29] op_sel:[0,0] op_sel_hi:[0,0]
	v_pk_mov_b32 v[86:87], v[28:29], v[26:27] op_sel:[1,1] op_sel_hi:[1,1]
	s_waitcnt lgkmcnt(0)
.LBB0_1375:
	v_max_u32_dpp v31, v72, v72 row_ror:1 row_mask:0xf bank_mask:0xf bound_ctrl:1
	v_max_u32_dpp v30, v76, v76 row_ror:1 row_mask:0xf bank_mask:0xf bound_ctrl:1
	v_max_u32_dpp v32, v80, v80 row_ror:1 row_mask:0xf bank_mask:0xf bound_ctrl:1
	v_max_u32_dpp v31, v31, v31 row_ror:2 row_mask:0xf bank_mask:0xf bound_ctrl:1
	v_max_u32_dpp v33, v84, v84 row_ror:1 row_mask:0xf bank_mask:0xf bound_ctrl:1
	v_max_u32_dpp v30, v30, v30 row_ror:2 row_mask:0xf bank_mask:0xf bound_ctrl:1
	v_max_u32_dpp v32, v32, v32 row_ror:2 row_mask:0xf bank_mask:0xf bound_ctrl:1
	v_max_u32_dpp v31, v31, v31 row_ror:4 row_mask:0xf bank_mask:0xf bound_ctrl:1
	v_max_u32_dpp v33, v33, v33 row_ror:2 row_mask:0xf bank_mask:0xf bound_ctrl:1
	v_max_u32_dpp v30, v30, v30 row_ror:4 row_mask:0xf bank_mask:0xf bound_ctrl:1
	v_max_u32_dpp v32, v32, v32 row_ror:4 row_mask:0xf bank_mask:0xf bound_ctrl:1
	v_max_u32_dpp v31, v31, v31 row_ror:8 row_mask:0xf bank_mask:0xf bound_ctrl:1
	v_max_u32_dpp v33, v33, v33 row_ror:4 row_mask:0xf bank_mask:0xf bound_ctrl:1
	v_max_u32_dpp v30, v30, v30 row_ror:8 row_mask:0xf bank_mask:0xf bound_ctrl:1
	v_max_u32_dpp v32, v32, v32 row_ror:8 row_mask:0xf bank_mask:0xf bound_ctrl:1
	v_max_u32_dpp v33, v33, v33 row_ror:8 row_mask:0xf bank_mask:0xf bound_ctrl:1
	v_cmp_eq_u32_e64 s[84:85], v72, v31
	v_cmp_eq_u32_e64 s[86:87], v76, v30
	v_cmp_eq_u32_e64 s[88:89], v80, v32
	v_cmp_eq_u32_e64 s[90:91], v84, v33
	s_mov_b64 exec, s[84:85]
	v_pk_mov_b32 v[72:73], v[72:73], v[74:75] op_sel:[1,0] op_sel_hi:[1,0]
	v_pk_mov_b32 v[74:75], v[74:75], v[70:71] op_sel:[1,0] op_sel_hi:[1,0]
	s_mov_b64 exec, s[86:87]
	v_pk_mov_b32 v[76:77], v[76:77], v[78:79] op_sel:[1,0] op_sel_hi:[1,0]
	v_pk_mov_b32 v[78:79], v[78:79], v[70:71] op_sel:[1,0] op_sel_hi:[1,0]
	s_mov_b64 exec, s[88:89]
	v_pk_mov_b32 v[80:81], v[80:81], v[82:83] op_sel:[1,0] op_sel_hi:[1,0]
	v_pk_mov_b32 v[82:83], v[82:83], v[70:71] op_sel:[1,0] op_sel_hi:[1,0]
	s_mov_b64 exec, s[90:91]
	v_pk_mov_b32 v[84:85], v[84:85], v[86:87] op_sel:[1,0] op_sel_hi:[1,0]
	v_pk_mov_b32 v[86:87], v[86:87], v[70:71] op_sel:[1,0] op_sel_hi:[1,0]
	s_lshl_b64 exec, s[78:79], s40
	s_add_i32 s40, s40, 1
	v_pk_mov_b32 v[4:5], v[32:33], v[32:33] op_sel:[1,0] op_sel_hi:[1,0]
	v_pk_mov_b32 v[6:7], v[30:31], v[30:31] op_sel:[1,0] op_sel_hi:[1,0]
	s_mov_b64 exec, -1
	s_cmp_lg_u32 s40, 8
	s_cbranch_scc1 .LBB0_1375
	v_max_u32_dpp v31, v72, v72 row_ror:1 row_mask:0xf bank_mask:0xf bound_ctrl:1
	v_max_u32_dpp v30, v76, v76 row_ror:1 row_mask:0xf bank_mask:0xf bound_ctrl:1
	v_max_u32_dpp v32, v80, v80 row_ror:1 row_mask:0xf bank_mask:0xf bound_ctrl:1
	v_max_u32_dpp v31, v31, v31 row_ror:2 row_mask:0xf bank_mask:0xf bound_ctrl:1
	v_max_u32_dpp v33, v84, v84 row_ror:1 row_mask:0xf bank_mask:0xf bound_ctrl:1
	v_max_u32_dpp v30, v30, v30 row_ror:2 row_mask:0xf bank_mask:0xf bound_ctrl:1
	v_max_u32_dpp v32, v32, v32 row_ror:2 row_mask:0xf bank_mask:0xf bound_ctrl:1
	v_max_u32_dpp v31, v31, v31 row_ror:4 row_mask:0xf bank_mask:0xf bound_ctrl:1
	v_max_u32_dpp v33, v33, v33 row_ror:2 row_mask:0xf bank_mask:0xf bound_ctrl:1
	v_max_u32_dpp v30, v30, v30 row_ror:4 row_mask:0xf bank_mask:0xf bound_ctrl:1
	v_max_u32_dpp v32, v32, v32 row_ror:4 row_mask:0xf bank_mask:0xf bound_ctrl:1
	v_max_u32_dpp v31, v31, v31 row_ror:8 row_mask:0xf bank_mask:0xf bound_ctrl:1
	v_max_u32_dpp v33, v33, v33 row_ror:4 row_mask:0xf bank_mask:0xf bound_ctrl:1
	v_max_u32_dpp v30, v30, v30 row_ror:8 row_mask:0xf bank_mask:0xf bound_ctrl:1
	v_max_u32_dpp v32, v32, v32 row_ror:8 row_mask:0xf bank_mask:0xf bound_ctrl:1
	v_max_u32_dpp v33, v33, v33 row_ror:8 row_mask:0xf bank_mask:0xf bound_ctrl:1
	v_cmp_eq_u32_e64 s[84:85], v72, v31
	v_cmp_eq_u32_e64 s[86:87], v76, v30
	v_cmp_eq_u32_e64 s[88:89], v80, v32
	v_cmp_eq_u32_e64 s[90:91], v84, v33
	s_mov_b64 exec, s[84:85]
	v_pk_mov_b32 v[72:73], v[72:73], v[74:75] op_sel:[1,0] op_sel_hi:[1,0]
	v_pk_mov_b32 v[74:75], v[74:75], v[70:71] op_sel:[1,0] op_sel_hi:[1,0]
	s_mov_b64 exec, s[86:87]
	v_pk_mov_b32 v[76:77], v[76:77], v[78:79] op_sel:[1,0] op_sel_hi:[1,0]
	v_pk_mov_b32 v[78:79], v[78:79], v[70:71] op_sel:[1,0] op_sel_hi:[1,0]
	s_mov_b64 exec, s[88:89]
	v_pk_mov_b32 v[80:81], v[80:81], v[82:83] op_sel:[1,0] op_sel_hi:[1,0]
	v_pk_mov_b32 v[82:83], v[82:83], v[70:71] op_sel:[1,0] op_sel_hi:[1,0]
	s_mov_b64 exec, s[90:91]
	v_pk_mov_b32 v[84:85], v[84:85], v[86:87] op_sel:[1,0] op_sel_hi:[1,0]
	v_pk_mov_b32 v[86:87], v[86:87], v[70:71] op_sel:[1,0] op_sel_hi:[1,0]
	s_lshl_b64 exec, s[78:79], s40
	s_add_i32 s40, s40, 1
	v_pk_mov_b32 v[4:5], v[32:33], v[32:33] op_sel:[1,0] op_sel_hi:[1,0]
	v_pk_mov_b32 v[6:7], v[30:31], v[30:31] op_sel:[1,0] op_sel_hi:[1,0]
	s_mov_b64 exec, -1
	v_max_u32_dpp v31, v72, v72 row_ror:1 row_mask:0xf bank_mask:0xf bound_ctrl:1
	v_max_u32_dpp v30, v76, v76 row_ror:1 row_mask:0xf bank_mask:0xf bound_ctrl:1
	v_max_u32_dpp v32, v80, v80 row_ror:1 row_mask:0xf bank_mask:0xf bound_ctrl:1
	v_max_u32_dpp v31, v31, v31 row_ror:2 row_mask:0xf bank_mask:0xf bound_ctrl:1
	v_max_u32_dpp v33, v84, v84 row_ror:1 row_mask:0xf bank_mask:0xf bound_ctrl:1
	v_max_u32_dpp v30, v30, v30 row_ror:2 row_mask:0xf bank_mask:0xf bound_ctrl:1
	v_max_u32_dpp v32, v32, v32 row_ror:2 row_mask:0xf bank_mask:0xf bound_ctrl:1
	v_max_u32_dpp v31, v31, v31 row_ror:4 row_mask:0xf bank_mask:0xf bound_ctrl:1
	v_max_u32_dpp v33, v33, v33 row_ror:2 row_mask:0xf bank_mask:0xf bound_ctrl:1
	v_max_u32_dpp v30, v30, v30 row_ror:4 row_mask:0xf bank_mask:0xf bound_ctrl:1
	v_max_u32_dpp v32, v32, v32 row_ror:4 row_mask:0xf bank_mask:0xf bound_ctrl:1
	v_max_u32_dpp v31, v31, v31 row_ror:8 row_mask:0xf bank_mask:0xf bound_ctrl:1
	v_max_u32_dpp v33, v33, v33 row_ror:4 row_mask:0xf bank_mask:0xf bound_ctrl:1
	v_max_u32_dpp v30, v30, v30 row_ror:8 row_mask:0xf bank_mask:0xf bound_ctrl:1
	v_max_u32_dpp v32, v32, v32 row_ror:8 row_mask:0xf bank_mask:0xf bound_ctrl:1
	v_max_u32_dpp v33, v33, v33 row_ror:8 row_mask:0xf bank_mask:0xf bound_ctrl:1
	v_cmp_eq_u32_e64 s[84:85], v72, v31
	v_cmp_eq_u32_e64 s[86:87], v76, v30
	v_cmp_eq_u32_e64 s[88:89], v80, v32
	v_cmp_eq_u32_e64 s[90:91], v84, v33
	s_mov_b64 exec, s[84:85]
	v_pk_mov_b32 v[72:73], v[72:73], v[74:75] op_sel:[1,0] op_sel_hi:[1,0]
	v_pk_mov_b32 v[74:75], v[74:75], v[70:71] op_sel:[1,0] op_sel_hi:[1,0]
	s_mov_b64 exec, s[86:87]
	v_pk_mov_b32 v[76:77], v[76:77], v[78:79] op_sel:[1,0] op_sel_hi:[1,0]
	v_pk_mov_b32 v[78:79], v[78:79], v[70:71] op_sel:[1,0] op_sel_hi:[1,0]
	s_mov_b64 exec, s[88:89]
	v_pk_mov_b32 v[80:81], v[80:81], v[82:83] op_sel:[1,0] op_sel_hi:[1,0]
	v_pk_mov_b32 v[82:83], v[82:83], v[70:71] op_sel:[1,0] op_sel_hi:[1,0]
	s_mov_b64 exec, s[90:91]
	v_pk_mov_b32 v[84:85], v[84:85], v[86:87] op_sel:[1,0] op_sel_hi:[1,0]
	v_pk_mov_b32 v[86:87], v[86:87], v[70:71] op_sel:[1,0] op_sel_hi:[1,0]
	s_lshl_b64 exec, s[78:79], s40
	s_add_i32 s40, s40, 1
	v_pk_mov_b32 v[4:5], v[32:33], v[32:33] op_sel:[1,0] op_sel_hi:[1,0]
	v_pk_mov_b32 v[6:7], v[30:31], v[30:31] op_sel:[1,0] op_sel_hi:[1,0]
	s_mov_b64 exec, -1
	v_max_u32_dpp v31, v72, v72 row_ror:1 row_mask:0xf bank_mask:0xf bound_ctrl:1
	v_max_u32_dpp v30, v76, v76 row_ror:1 row_mask:0xf bank_mask:0xf bound_ctrl:1
	v_max_u32_dpp v32, v80, v80 row_ror:1 row_mask:0xf bank_mask:0xf bound_ctrl:1
	v_max_u32_dpp v31, v31, v31 row_ror:2 row_mask:0xf bank_mask:0xf bound_ctrl:1
	v_max_u32_dpp v33, v84, v84 row_ror:1 row_mask:0xf bank_mask:0xf bound_ctrl:1
	v_max_u32_dpp v30, v30, v30 row_ror:2 row_mask:0xf bank_mask:0xf bound_ctrl:1
	v_max_u32_dpp v32, v32, v32 row_ror:2 row_mask:0xf bank_mask:0xf bound_ctrl:1
	v_max_u32_dpp v31, v31, v31 row_ror:4 row_mask:0xf bank_mask:0xf bound_ctrl:1
	v_max_u32_dpp v33, v33, v33 row_ror:2 row_mask:0xf bank_mask:0xf bound_ctrl:1
	v_max_u32_dpp v30, v30, v30 row_ror:4 row_mask:0xf bank_mask:0xf bound_ctrl:1
	v_max_u32_dpp v32, v32, v32 row_ror:4 row_mask:0xf bank_mask:0xf bound_ctrl:1
	v_max_u32_dpp v31, v31, v31 row_ror:8 row_mask:0xf bank_mask:0xf bound_ctrl:1
	v_max_u32_dpp v33, v33, v33 row_ror:4 row_mask:0xf bank_mask:0xf bound_ctrl:1
	v_max_u32_dpp v30, v30, v30 row_ror:8 row_mask:0xf bank_mask:0xf bound_ctrl:1
	v_max_u32_dpp v32, v32, v32 row_ror:8 row_mask:0xf bank_mask:0xf bound_ctrl:1
	v_max_u32_dpp v33, v33, v33 row_ror:8 row_mask:0xf bank_mask:0xf bound_ctrl:1
	v_cmp_eq_u32_e64 s[84:85], v72, v31
	v_cmp_eq_u32_e64 s[86:87], v76, v30
	v_cmp_eq_u32_e64 s[88:89], v80, v32
	v_cmp_eq_u32_e64 s[90:91], v84, v33
	s_mov_b64 exec, s[84:85]
	v_pk_mov_b32 v[72:73], v[72:73], v[74:75] op_sel:[1,0] op_sel_hi:[1,0]
	v_pk_mov_b32 v[74:75], v[74:75], v[70:71] op_sel:[1,0] op_sel_hi:[1,0]
	s_mov_b64 exec, s[86:87]
	v_pk_mov_b32 v[76:77], v[76:77], v[78:79] op_sel:[1,0] op_sel_hi:[1,0]
	v_pk_mov_b32 v[78:79], v[78:79], v[70:71] op_sel:[1,0] op_sel_hi:[1,0]
	s_mov_b64 exec, s[88:89]
	v_pk_mov_b32 v[80:81], v[80:81], v[82:83] op_sel:[1,0] op_sel_hi:[1,0]
	v_pk_mov_b32 v[82:83], v[82:83], v[70:71] op_sel:[1,0] op_sel_hi:[1,0]
	s_mov_b64 exec, s[90:91]
	v_pk_mov_b32 v[84:85], v[84:85], v[86:87] op_sel:[1,0] op_sel_hi:[1,0]
	v_pk_mov_b32 v[86:87], v[86:87], v[70:71] op_sel:[1,0] op_sel_hi:[1,0]
	s_lshl_b64 exec, s[78:79], s40
	s_add_i32 s40, s40, 1
	v_pk_mov_b32 v[4:5], v[32:33], v[32:33] op_sel:[1,0] op_sel_hi:[1,0]
	v_pk_mov_b32 v[6:7], v[30:31], v[30:31] op_sel:[1,0] op_sel_hi:[1,0]
	s_mov_b64 exec, -1
	v_max_u32_dpp v31, v72, v72 row_ror:1 row_mask:0xf bank_mask:0xf bound_ctrl:1
	v_max_u32_dpp v30, v76, v76 row_ror:1 row_mask:0xf bank_mask:0xf bound_ctrl:1
	v_max_u32_dpp v32, v80, v80 row_ror:1 row_mask:0xf bank_mask:0xf bound_ctrl:1
	v_max_u32_dpp v31, v31, v31 row_ror:2 row_mask:0xf bank_mask:0xf bound_ctrl:1
	v_max_u32_dpp v33, v84, v84 row_ror:1 row_mask:0xf bank_mask:0xf bound_ctrl:1
	v_max_u32_dpp v30, v30, v30 row_ror:2 row_mask:0xf bank_mask:0xf bound_ctrl:1
	v_max_u32_dpp v32, v32, v32 row_ror:2 row_mask:0xf bank_mask:0xf bound_ctrl:1
	v_max_u32_dpp v31, v31, v31 row_ror:4 row_mask:0xf bank_mask:0xf bound_ctrl:1
	v_max_u32_dpp v33, v33, v33 row_ror:2 row_mask:0xf bank_mask:0xf bound_ctrl:1
	v_max_u32_dpp v30, v30, v30 row_ror:4 row_mask:0xf bank_mask:0xf bound_ctrl:1
	v_max_u32_dpp v32, v32, v32 row_ror:4 row_mask:0xf bank_mask:0xf bound_ctrl:1
	v_max_u32_dpp v31, v31, v31 row_ror:8 row_mask:0xf bank_mask:0xf bound_ctrl:1
	v_max_u32_dpp v33, v33, v33 row_ror:4 row_mask:0xf bank_mask:0xf bound_ctrl:1
	v_max_u32_dpp v30, v30, v30 row_ror:8 row_mask:0xf bank_mask:0xf bound_ctrl:1
	v_max_u32_dpp v32, v32, v32 row_ror:8 row_mask:0xf bank_mask:0xf bound_ctrl:1
	v_max_u32_dpp v33, v33, v33 row_ror:8 row_mask:0xf bank_mask:0xf bound_ctrl:1
	v_cmp_eq_u32_e64 s[84:85], v72, v31
	v_cmp_eq_u32_e64 s[86:87], v76, v30
	v_cmp_eq_u32_e64 s[88:89], v80, v32
	v_cmp_eq_u32_e64 s[90:91], v84, v33
	s_mov_b64 exec, s[84:85]
	v_pk_mov_b32 v[72:73], v[72:73], v[74:75] op_sel:[1,0] op_sel_hi:[1,0]
	v_pk_mov_b32 v[74:75], v[74:75], v[70:71] op_sel:[1,0] op_sel_hi:[1,0]
	s_mov_b64 exec, s[86:87]
	v_pk_mov_b32 v[76:77], v[76:77], v[78:79] op_sel:[1,0] op_sel_hi:[1,0]
	v_pk_mov_b32 v[78:79], v[78:79], v[70:71] op_sel:[1,0] op_sel_hi:[1,0]
	s_mov_b64 exec, s[88:89]
	v_pk_mov_b32 v[80:81], v[80:81], v[82:83] op_sel:[1,0] op_sel_hi:[1,0]
	v_pk_mov_b32 v[82:83], v[82:83], v[70:71] op_sel:[1,0] op_sel_hi:[1,0]
	s_mov_b64 exec, s[90:91]
	v_pk_mov_b32 v[84:85], v[84:85], v[86:87] op_sel:[1,0] op_sel_hi:[1,0]
	v_pk_mov_b32 v[86:87], v[86:87], v[70:71] op_sel:[1,0] op_sel_hi:[1,0]
	s_lshl_b64 exec, s[78:79], s40
	s_add_i32 s40, s40, 1
	v_pk_mov_b32 v[4:5], v[32:33], v[32:33] op_sel:[1,0] op_sel_hi:[1,0]
	v_pk_mov_b32 v[6:7], v[30:31], v[30:31] op_sel:[1,0] op_sel_hi:[1,0]
	s_mov_b64 exec, -1
	v_max_u32_dpp v31, v72, v72 row_ror:1 row_mask:0xf bank_mask:0xf bound_ctrl:1
	v_max_u32_dpp v30, v76, v76 row_ror:1 row_mask:0xf bank_mask:0xf bound_ctrl:1
	v_max_u32_dpp v32, v80, v80 row_ror:1 row_mask:0xf bank_mask:0xf bound_ctrl:1
	v_max_u32_dpp v31, v31, v31 row_ror:2 row_mask:0xf bank_mask:0xf bound_ctrl:1
	v_max_u32_dpp v33, v84, v84 row_ror:1 row_mask:0xf bank_mask:0xf bound_ctrl:1
	v_max_u32_dpp v30, v30, v30 row_ror:2 row_mask:0xf bank_mask:0xf bound_ctrl:1
	v_max_u32_dpp v32, v32, v32 row_ror:2 row_mask:0xf bank_mask:0xf bound_ctrl:1
	v_max_u32_dpp v31, v31, v31 row_ror:4 row_mask:0xf bank_mask:0xf bound_ctrl:1
	v_max_u32_dpp v33, v33, v33 row_ror:2 row_mask:0xf bank_mask:0xf bound_ctrl:1
	v_max_u32_dpp v30, v30, v30 row_ror:4 row_mask:0xf bank_mask:0xf bound_ctrl:1
	v_max_u32_dpp v32, v32, v32 row_ror:4 row_mask:0xf bank_mask:0xf bound_ctrl:1
	v_max_u32_dpp v31, v31, v31 row_ror:8 row_mask:0xf bank_mask:0xf bound_ctrl:1
	v_max_u32_dpp v33, v33, v33 row_ror:4 row_mask:0xf bank_mask:0xf bound_ctrl:1
	v_max_u32_dpp v30, v30, v30 row_ror:8 row_mask:0xf bank_mask:0xf bound_ctrl:1
	v_max_u32_dpp v32, v32, v32 row_ror:8 row_mask:0xf bank_mask:0xf bound_ctrl:1
	v_max_u32_dpp v33, v33, v33 row_ror:8 row_mask:0xf bank_mask:0xf bound_ctrl:1
	v_cmp_eq_u32_e64 s[84:85], v72, v31
	v_cmp_eq_u32_e64 s[86:87], v76, v30
	v_cmp_eq_u32_e64 s[88:89], v80, v32
	v_cmp_eq_u32_e64 s[90:91], v84, v33
	s_mov_b64 exec, s[84:85]
	v_pk_mov_b32 v[72:73], v[72:73], v[74:75] op_sel:[1,0] op_sel_hi:[1,0]
	v_pk_mov_b32 v[74:75], v[74:75], v[70:71] op_sel:[1,0] op_sel_hi:[1,0]
	s_mov_b64 exec, s[86:87]
	v_pk_mov_b32 v[76:77], v[76:77], v[78:79] op_sel:[1,0] op_sel_hi:[1,0]
	v_pk_mov_b32 v[78:79], v[78:79], v[70:71] op_sel:[1,0] op_sel_hi:[1,0]
	s_mov_b64 exec, s[88:89]
	v_pk_mov_b32 v[80:81], v[80:81], v[82:83] op_sel:[1,0] op_sel_hi:[1,0]
	v_pk_mov_b32 v[82:83], v[82:83], v[70:71] op_sel:[1,0] op_sel_hi:[1,0]
	s_mov_b64 exec, s[90:91]
	v_pk_mov_b32 v[84:85], v[84:85], v[86:87] op_sel:[1,0] op_sel_hi:[1,0]
	v_pk_mov_b32 v[86:87], v[86:87], v[70:71] op_sel:[1,0] op_sel_hi:[1,0]
	s_lshl_b64 exec, s[78:79], s40
	s_add_i32 s40, s40, 1
	v_pk_mov_b32 v[4:5], v[32:33], v[32:33] op_sel:[1,0] op_sel_hi:[1,0]
	v_pk_mov_b32 v[6:7], v[30:31], v[30:31] op_sel:[1,0] op_sel_hi:[1,0]
	s_mov_b64 exec, -1
	v_max_u32_dpp v31, v72, v72 row_ror:1 row_mask:0xf bank_mask:0xf bound_ctrl:1
	v_max_u32_dpp v30, v76, v76 row_ror:1 row_mask:0xf bank_mask:0xf bound_ctrl:1
	v_max_u32_dpp v32, v80, v80 row_ror:1 row_mask:0xf bank_mask:0xf bound_ctrl:1
	v_max_u32_dpp v31, v31, v31 row_ror:2 row_mask:0xf bank_mask:0xf bound_ctrl:1
	v_max_u32_dpp v33, v84, v84 row_ror:1 row_mask:0xf bank_mask:0xf bound_ctrl:1
	v_max_u32_dpp v30, v30, v30 row_ror:2 row_mask:0xf bank_mask:0xf bound_ctrl:1
	v_max_u32_dpp v32, v32, v32 row_ror:2 row_mask:0xf bank_mask:0xf bound_ctrl:1
	v_max_u32_dpp v31, v31, v31 row_ror:4 row_mask:0xf bank_mask:0xf bound_ctrl:1
	v_max_u32_dpp v33, v33, v33 row_ror:2 row_mask:0xf bank_mask:0xf bound_ctrl:1
	v_max_u32_dpp v30, v30, v30 row_ror:4 row_mask:0xf bank_mask:0xf bound_ctrl:1
	v_max_u32_dpp v32, v32, v32 row_ror:4 row_mask:0xf bank_mask:0xf bound_ctrl:1
	v_max_u32_dpp v31, v31, v31 row_ror:8 row_mask:0xf bank_mask:0xf bound_ctrl:1
	v_max_u32_dpp v33, v33, v33 row_ror:4 row_mask:0xf bank_mask:0xf bound_ctrl:1
	v_max_u32_dpp v30, v30, v30 row_ror:8 row_mask:0xf bank_mask:0xf bound_ctrl:1
	v_max_u32_dpp v32, v32, v32 row_ror:8 row_mask:0xf bank_mask:0xf bound_ctrl:1
	v_max_u32_dpp v33, v33, v33 row_ror:8 row_mask:0xf bank_mask:0xf bound_ctrl:1
	v_cmp_eq_u32_e64 s[84:85], v72, v31
	v_cmp_eq_u32_e64 s[86:87], v76, v30
	v_cmp_eq_u32_e64 s[88:89], v80, v32
	v_cmp_eq_u32_e64 s[90:91], v84, v33
	s_mov_b64 exec, s[84:85]
	v_pk_mov_b32 v[72:73], v[72:73], v[74:75] op_sel:[1,0] op_sel_hi:[1,0]
	s_mov_b64 exec, s[86:87]
	v_pk_mov_b32 v[76:77], v[76:77], v[78:79] op_sel:[1,0] op_sel_hi:[1,0]
	s_mov_b64 exec, s[88:89]
	v_pk_mov_b32 v[80:81], v[80:81], v[82:83] op_sel:[1,0] op_sel_hi:[1,0]
	s_mov_b64 exec, s[90:91]
	v_pk_mov_b32 v[84:85], v[84:85], v[86:87] op_sel:[1,0] op_sel_hi:[1,0]
	s_lshl_b64 exec, s[78:79], s40
	s_add_i32 s40, s40, 1
	v_pk_mov_b32 v[4:5], v[32:33], v[32:33] op_sel:[1,0] op_sel_hi:[1,0]
	v_pk_mov_b32 v[6:7], v[30:31], v[30:31] op_sel:[1,0] op_sel_hi:[1,0]
	s_mov_b64 exec, -1
	v_max_u32_dpp v31, v72, v72 row_ror:1 row_mask:0xf bank_mask:0xf bound_ctrl:1
	v_max_u32_dpp v30, v76, v76 row_ror:1 row_mask:0xf bank_mask:0xf bound_ctrl:1
	v_max_u32_dpp v32, v80, v80 row_ror:1 row_mask:0xf bank_mask:0xf bound_ctrl:1
	v_max_u32_dpp v31, v31, v31 row_ror:2 row_mask:0xf bank_mask:0xf bound_ctrl:1
	v_max_u32_dpp v33, v84, v84 row_ror:1 row_mask:0xf bank_mask:0xf bound_ctrl:1
	v_max_u32_dpp v30, v30, v30 row_ror:2 row_mask:0xf bank_mask:0xf bound_ctrl:1
	v_max_u32_dpp v32, v32, v32 row_ror:2 row_mask:0xf bank_mask:0xf bound_ctrl:1
	v_max_u32_dpp v31, v31, v31 row_ror:4 row_mask:0xf bank_mask:0xf bound_ctrl:1
	v_max_u32_dpp v33, v33, v33 row_ror:2 row_mask:0xf bank_mask:0xf bound_ctrl:1
	v_max_u32_dpp v30, v30, v30 row_ror:4 row_mask:0xf bank_mask:0xf bound_ctrl:1
	v_max_u32_dpp v32, v32, v32 row_ror:4 row_mask:0xf bank_mask:0xf bound_ctrl:1
	v_max_u32_dpp v31, v31, v31 row_ror:8 row_mask:0xf bank_mask:0xf bound_ctrl:1
	v_max_u32_dpp v33, v33, v33 row_ror:4 row_mask:0xf bank_mask:0xf bound_ctrl:1
	v_max_u32_dpp v30, v30, v30 row_ror:8 row_mask:0xf bank_mask:0xf bound_ctrl:1
	v_max_u32_dpp v32, v32, v32 row_ror:8 row_mask:0xf bank_mask:0xf bound_ctrl:1
	v_max_u32_dpp v33, v33, v33 row_ror:8 row_mask:0xf bank_mask:0xf bound_ctrl:1
	v_cmp_eq_u32_e64 s[84:85], v72, v31
	v_cmp_eq_u32_e64 s[86:87], v76, v30
	v_cmp_eq_u32_e64 s[88:89], v80, v32
	v_cmp_eq_u32_e64 s[90:91], v84, v33
	s_mov_b64 exec, s[84:85]
	v_pk_mov_b32 v[72:73], v[72:73], v[74:75] op_sel:[1,0] op_sel_hi:[1,0]
	s_mov_b64 exec, s[86:87]
	v_pk_mov_b32 v[76:77], v[76:77], v[78:79] op_sel:[1,0] op_sel_hi:[1,0]
	s_mov_b64 exec, s[88:89]
	v_pk_mov_b32 v[80:81], v[80:81], v[82:83] op_sel:[1,0] op_sel_hi:[1,0]
	s_mov_b64 exec, s[90:91]
	v_pk_mov_b32 v[84:85], v[84:85], v[86:87] op_sel:[1,0] op_sel_hi:[1,0]
	s_lshl_b64 exec, s[78:79], s40
	s_add_i32 s40, s40, 1
	v_pk_mov_b32 v[4:5], v[32:33], v[32:33] op_sel:[1,0] op_sel_hi:[1,0]
	v_pk_mov_b32 v[6:7], v[30:31], v[30:31] op_sel:[1,0] op_sel_hi:[1,0]
	s_mov_b64 exec, -1
	v_max_u32_dpp v31, v72, v72 row_ror:1 row_mask:0xf bank_mask:0xf bound_ctrl:1
	v_max_u32_dpp v30, v76, v76 row_ror:1 row_mask:0xf bank_mask:0xf bound_ctrl:1
	v_max_u32_dpp v32, v80, v80 row_ror:1 row_mask:0xf bank_mask:0xf bound_ctrl:1
	v_max_u32_dpp v31, v31, v31 row_ror:2 row_mask:0xf bank_mask:0xf bound_ctrl:1
	v_max_u32_dpp v33, v84, v84 row_ror:1 row_mask:0xf bank_mask:0xf bound_ctrl:1
	v_max_u32_dpp v30, v30, v30 row_ror:2 row_mask:0xf bank_mask:0xf bound_ctrl:1
	v_max_u32_dpp v32, v32, v32 row_ror:2 row_mask:0xf bank_mask:0xf bound_ctrl:1
	v_max_u32_dpp v31, v31, v31 row_ror:4 row_mask:0xf bank_mask:0xf bound_ctrl:1
	v_max_u32_dpp v33, v33, v33 row_ror:2 row_mask:0xf bank_mask:0xf bound_ctrl:1
	v_max_u32_dpp v30, v30, v30 row_ror:4 row_mask:0xf bank_mask:0xf bound_ctrl:1
	v_max_u32_dpp v32, v32, v32 row_ror:4 row_mask:0xf bank_mask:0xf bound_ctrl:1
	v_max_u32_dpp v31, v31, v31 row_ror:8 row_mask:0xf bank_mask:0xf bound_ctrl:1
	v_max_u32_dpp v33, v33, v33 row_ror:4 row_mask:0xf bank_mask:0xf bound_ctrl:1
	v_max_u32_dpp v30, v30, v30 row_ror:8 row_mask:0xf bank_mask:0xf bound_ctrl:1
	v_max_u32_dpp v32, v32, v32 row_ror:8 row_mask:0xf bank_mask:0xf bound_ctrl:1
	v_max_u32_dpp v33, v33, v33 row_ror:8 row_mask:0xf bank_mask:0xf bound_ctrl:1
	s_lshl_b64 exec, s[78:79], s40
	v_pk_mov_b32 v[4:5], v[32:33], v[32:33] op_sel:[1,0] op_sel_hi:[1,0]
	v_pk_mov_b32 v[6:7], v[30:31], v[30:31] op_sel:[1,0] op_sel_hi:[1,0]
	s_mov_b64 exec, -1
	v_max_u32_dpp v15, v7, v7 row_ror:1 row_mask:0xf bank_mask:0xf bound_ctrl:1
	v_cmp_lt_i32_e32 vcc, -1, v7
	v_bitop3_b32 v11, v18, s60, v18 bitop3:0xc
	v_max_u32_dpp v15, v15, v15 row_ror:2 row_mask:0xf bank_mask:0xf bound_ctrl:1
	v_cndmask_b32_e64 v14, v217, -1, vcc
	v_bitop3_b32 v14, v14, v7, s59 bitop3:0x78
	v_max_u32_dpp v15, v15, v15 row_ror:4 row_mask:0xf bank_mask:0xf bound_ctrl:1
	v_not_b32_e32 v13, v7
	v_lshrrev_b32_e32 v13, 4, v13
	v_max_u32_dpp v15, v15, v15 row_ror:8 row_mask:0xf bank_mask:0xf bound_ctrl:1
	v_cmp_lt_i32_e32 vcc, -1, v15
	v_and_or_b32 v13, v13, 15, v195
	v_lshlrev_b32_e32 v13, 2, v13
	v_cndmask_b32_e64 v18, v217, -1, vcc
	v_bitop3_b32 v15, v18, v15, s59 bitop3:0x78
	v_sub_f32_e32 v14, v14, v15
	v_mul_f32_e32 v14, 0x3fb8aa3b, v14
	v_exp_f32_e32 v14, v14
	ds_bpermute_b32 v11, v13, v11
	v_bitop3_b32 v7, v7, v195, 15 bitop3:0xce
	v_bitop3_b32 v0, v0, s60, v0 bitop3:0xc
	v_add_f32_dpp v13, v14, v14 row_ror:1 row_mask:0xf bank_mask:0xf bound_ctrl:1
	v_lshlrev_b32_e32 v7, 2, v7
	ds_bpermute_b32 v0, v7, v0
	v_add_f32_dpp v13, v13, v13 row_ror:2 row_mask:0xf bank_mask:0xf bound_ctrl:1
	v_bitop3_b32 v10, v19, s60, v19 bitop3:0xc
	v_bitop3_b32 v9, v20, s60, v20 bitop3:0xc
	v_add_f32_dpp v13, v13, v13 row_ror:4 row_mask:0xf bank_mask:0xf bound_ctrl:1
	v_lshl_or_b32 v12, s33, 4, v171
	s_waitcnt lgkmcnt(0)
	v_lshl_add_u32 v0, v11, 7, v0
	v_add_f32_dpp v13, v13, v13 row_ror:8 row_mask:0xf bank_mask:0xf bound_ctrl:1
	v_div_scale_f32 v15, s[0:1], v13, v13, v14
	v_rcp_f32_e32 v18, v15
	v_bitop3_b32 v1, v1, s60, v1 bitop3:0xc
	v_bitop3_b32 v2, v2, s60, v2 bitop3:0xc
	v_bitop3_b32 v3, v3, s60, v3 bitop3:0xc
	v_fma_f32 v7, -v15, v18, 1.0
	v_fmac_f32_e32 v18, v7, v18
	v_div_scale_f32 v7, vcc, v14, v13, v14
	v_mul_f32_e32 v19, v7, v18
	v_fma_f32 v20, -v15, v19, v7
	v_fmac_f32_e32 v19, v20, v18
	v_fma_f32 v7, -v15, v19, v7
	v_div_fmas_f32 v7, v7, v18, v19
	v_div_fixup_f32 v7, v7, v13, v14
	v_or_b32_e32 v13, v12, v183
	v_lshl_add_u32 v11, v13, 1, s63
	v_cvt_f16_f32_e32 v7, v7
	v_max_u32_dpp v13, v6, v6 row_ror:1 row_mask:0xf bank_mask:0xf bound_ctrl:1
	v_cmp_lt_i32_e32 vcc, -1, v6
	ds_write_b16 v11, v0
	ds_write_b16 v11, v7 offset:32768
	v_max_u32_dpp v13, v13, v13 row_ror:2 row_mask:0xf bank_mask:0xf bound_ctrl:1
	v_cndmask_b32_e64 v7, v217, -1, vcc
	v_bitop3_b32 v7, v7, v6, s59 bitop3:0x78
	v_max_u32_dpp v13, v13, v13 row_ror:4 row_mask:0xf bank_mask:0xf bound_ctrl:1
	v_not_b32_e32 v0, v6
	v_lshrrev_b32_e32 v0, 4, v0
	v_max_u32_dpp v13, v13, v13 row_ror:8 row_mask:0xf bank_mask:0xf bound_ctrl:1
	v_cmp_lt_i32_e32 vcc, -1, v13
	v_and_or_b32 v0, v0, 15, v195
	v_lshlrev_b32_e32 v0, 2, v0
	v_cndmask_b32_e64 v14, v217, -1, vcc
	v_bitop3_b32 v13, v14, v13, s59 bitop3:0x78
	v_sub_f32_e32 v7, v7, v13
	v_mul_f32_e32 v7, 0x3fb8aa3b, v7
	v_exp_f32_e32 v7, v7
	ds_bpermute_b32 v0, v0, v10
	v_bitop3_b32 v6, v6, v195, 15 bitop3:0xce
	v_lshlrev_b32_e32 v6, 2, v6
	v_add_f32_dpp v10, v7, v7 row_ror:1 row_mask:0xf bank_mask:0xf bound_ctrl:1
	ds_bpermute_b32 v1, v6, v1
	v_bitop3_b32 v8, v21, s60, v21 bitop3:0xc
	v_add_f32_dpp v10, v10, v10 row_ror:2 row_mask:0xf bank_mask:0xf bound_ctrl:1
	s_waitcnt lgkmcnt(0)
	v_lshl_add_u32 v0, v0, 7, v1
	v_add_f32_dpp v10, v10, v10 row_ror:4 row_mask:0xf bank_mask:0xf bound_ctrl:1
	ds_write_b16 v11, v0 offset:256
	v_not_b32_e32 v1, v5
	v_add_f32_dpp v10, v10, v10 row_ror:8 row_mask:0xf bank_mask:0xf bound_ctrl:1
	v_div_scale_f32 v13, s[0:1], v10, v10, v7
	v_rcp_f32_e32 v14, v13
	v_lshrrev_b32_e32 v1, 4, v1
	v_and_or_b32 v1, v1, 15, v195
	v_lshlrev_b32_e32 v1, 2, v1
	v_fma_f32 v6, -v13, v14, 1.0
	v_fmac_f32_e32 v14, v6, v14
	v_div_scale_f32 v6, vcc, v7, v10, v7
	v_mul_f32_e32 v15, v6, v14
	v_fma_f32 v18, -v13, v15, v6
	v_fmac_f32_e32 v15, v18, v14
	v_fma_f32 v6, -v13, v15, v6
	v_div_fmas_f32 v6, v6, v14, v15
	v_div_fixup_f32 v6, v6, v10, v7
	v_max_u32_dpp v7, v5, v5 row_ror:1 row_mask:0xf bank_mask:0xf bound_ctrl:1
	v_cmp_lt_i32_e32 vcc, -1, v5
	v_cvt_f16_f32_e32 v0, v6
	v_max_u32_dpp v7, v7, v7 row_ror:2 row_mask:0xf bank_mask:0xf bound_ctrl:1
	v_cndmask_b32_e64 v6, v217, -1, vcc
	v_bitop3_b32 v6, v6, v5, s59 bitop3:0x78
	v_max_u32_dpp v7, v7, v7 row_ror:4 row_mask:0xf bank_mask:0xf bound_ctrl:1
	ds_bpermute_b32 v1, v1, v9
	v_bitop3_b32 v5, v5, v195, 15 bitop3:0xce
	v_max_u32_dpp v7, v7, v7 row_ror:8 row_mask:0xf bank_mask:0xf bound_ctrl:1
	v_cmp_lt_i32_e32 vcc, -1, v7
	v_lshlrev_b32_e32 v5, 2, v5
	ds_bpermute_b32 v2, v5, v2
	v_cndmask_b32_e64 v10, v217, -1, vcc
	v_bitop3_b32 v7, v10, v7, s59 bitop3:0x78
	v_sub_f32_e32 v6, v6, v7
	v_mul_f32_e32 v6, 0x3fb8aa3b, v6
	v_exp_f32_e32 v6, v6
	ds_write_b16 v11, v0 offset:33024
	s_waitcnt lgkmcnt(1)
	v_lshl_add_u32 v0, v1, 7, v2
	v_max_u32_dpp v2, v4, v4 row_ror:1 row_mask:0xf bank_mask:0xf bound_ctrl:1
	v_add_f32_dpp v7, v6, v6 row_ror:1 row_mask:0xf bank_mask:0xf bound_ctrl:1
	s_nop 0
	v_max_u32_dpp v2, v2, v2 row_ror:2 row_mask:0xf bank_mask:0xf bound_ctrl:1
	v_add_f32_dpp v7, v7, v7 row_ror:2 row_mask:0xf bank_mask:0xf bound_ctrl:1
	s_nop 0
	v_max_u32_dpp v2, v2, v2 row_ror:4 row_mask:0xf bank_mask:0xf bound_ctrl:1
	v_add_f32_dpp v7, v7, v7 row_ror:4 row_mask:0xf bank_mask:0xf bound_ctrl:1
	s_nop 0
	v_max_u32_dpp v2, v2, v2 row_ror:8 row_mask:0xf bank_mask:0xf bound_ctrl:1
	v_add_f32_dpp v7, v7, v7 row_ror:8 row_mask:0xf bank_mask:0xf bound_ctrl:1
	v_div_scale_f32 v9, s[0:1], v7, v7, v6
	v_rcp_f32_e32 v10, v9
	s_nop 0
	v_fma_f32 v5, -v9, v10, 1.0
	v_fmac_f32_e32 v10, v5, v10
	v_div_scale_f32 v5, vcc, v6, v7, v6
	v_mul_f32_e32 v13, v5, v10
	v_fma_f32 v14, -v9, v13, v5
	v_fmac_f32_e32 v13, v14, v10
	v_fma_f32 v5, -v9, v13, v5
	v_div_fmas_f32 v5, v5, v10, v13
	v_div_fixup_f32 v5, v5, v7, v6
	v_cvt_f16_f32_e32 v5, v5
	v_cmp_lt_i32_e32 vcc, -1, v4
	ds_write_b16 v11, v0 offset:512
	ds_write_b16 v11, v5 offset:33280
	v_cndmask_b32_e64 v1, v217, -1, vcc
	v_cmp_lt_i32_e32 vcc, -1, v2
	v_bitop3_b32 v1, v1, v4, s59 bitop3:0x78
	v_not_b32_e32 v0, v4
	v_cndmask_b32_e64 v5, v217, -1, vcc
	v_bitop3_b32 v2, v5, v2, s59 bitop3:0x78
	v_sub_f32_e32 v1, v1, v2
	v_mul_f32_e32 v1, 0x3fb8aa3b, v1
	v_exp_f32_e32 v1, v1
	v_bitop3_b32 v4, v4, v195, 15 bitop3:0xce
	v_lshlrev_b32_e32 v4, 2, v4
	v_lshrrev_b32_e32 v0, 4, v0
	v_add_f32_dpp v2, v1, v1 row_ror:1 row_mask:0xf bank_mask:0xf bound_ctrl:1
	ds_bpermute_b32 v3, v4, v3
	v_and_or_b32 v0, v0, 15, v195
	v_add_f32_dpp v2, v2, v2 row_ror:2 row_mask:0xf bank_mask:0xf bound_ctrl:1
	v_lshlrev_b32_e32 v0, 2, v0
	ds_bpermute_b32 v0, v0, v8
	v_add_f32_dpp v2, v2, v2 row_ror:4 row_mask:0xf bank_mask:0xf bound_ctrl:1
	s_waitcnt lgkmcnt(0)
	v_lshl_add_u32 v0, v0, 7, v3
	v_add_f32_dpp v2, v2, v2 row_ror:8 row_mask:0xf bank_mask:0xf bound_ctrl:1
	v_div_scale_f32 v5, s[0:1], v2, v2, v1
	v_rcp_f32_e32 v6, v5
	s_add_i32 s0, s33, 1
	s_cmp_lg_u32 s33, 7
	s_cselect_b32 s1, s0, 7
	v_fma_f32 v4, -v5, v6, 1.0
	v_fmac_f32_e32 v6, v4, v6
	v_div_scale_f32 v4, vcc, v1, v2, v1
	v_mul_f32_e32 v7, v4, v6
	v_fma_f32 v8, -v5, v7, v4
	v_fmac_f32_e32 v7, v8, v6
	v_fma_f32 v4, -v5, v7, v4
	v_div_fmas_f32 v4, v4, v6, v7
	v_div_fixup_f32 v1, v4, v2, v1
	v_add_u32_e32 v2, v12, v182
	v_cvt_f16_f32_e32 v1, v1
	v_lshl_or_b32 v2, v2, 1, v218
	s_lshl_b32 s40, s1, 16
	v_add_u32_e32 v2, s63, v2
	s_cmp_lt_u32 s1, 4
	ds_write_b16 v2, v0
	ds_write_b16 v2, v1 offset:32768
	v_lshl_add_u64 v[0:1], v[154:155], 0, s[40:41]
	s_cselect_b32 s33, s3, s56
	s_cselect_b32 s40, s2, s55
	v_mov_b32_e32 v2, s40
	v_mov_b32_e32 v3, s33
	s_lshl_b32 s1, s1, 9
	v_lshl_add_u64 v[2:3], v[16:17], 1, v[2:3]
	s_and_b32 s40, s1, 0x600
	v_lshl_add_u64 v[2:3], v[2:3], 0, s[40:41]
	v_lshl_add_u64 v[12:13], v[2:3], 0, v[148:149]
	s_cmp_eq_u32 s0, 8
	s_mov_b32 s33, s0
	s_cbranch_scc0 .LBB0_1346
	s_waitcnt lgkmcnt(0)
	s_barrier
	ds_read_b128 v[0:3], v185
	ds_read_b128 v[40:43], v185 offset:16
	s_ashr_i32 s49, s48, 31
	s_lshl_b64 s[0:1], s[48:49], 10
	v_lshl_add_u64 v[144:145], v[152:153], 0, s[0:1]
	s_waitcnt lgkmcnt(1)
	v_lshlrev_b32_e32 v4, 7, v0
	v_bfe_u32 v0, v0, 16, 16
	v_and_or_b32 v64, v4, s68, v150
	v_lshl_or_b32 v0, v0, 7, v150
	v_lshlrev_b32_e32 v4, 7, v1
	v_and_or_b32 v4, v4, s68, v150
	global_load_dwordx4 v[60:63], v0, s[26:27]
	global_load_dwordx4 v[56:59], v4, s[26:27]
	v_bfe_u32 v0, v1, 16, 16
	v_lshl_or_b32 v0, v0, 7, v150
	v_lshlrev_b32_e32 v1, 7, v2
	v_and_or_b32 v1, v1, s68, v150
	global_load_dwordx4 v[52:55], v0, s[26:27]
	global_load_dwordx4 v[48:51], v1, s[26:27]
	v_bfe_u32 v0, v2, 16, 16
	v_lshl_or_b32 v0, v0, 7, v150
	v_lshlrev_b32_e32 v1, 7, v3
	v_and_or_b32 v1, v1, s68, v150
	global_load_dwordx4 v[44:47], v0, s[26:27]
	global_load_dwordx4 v[36:39], v1, s[26:27]
	v_bfe_u32 v0, v3, 16, 16
	v_lshl_or_b32 v0, v0, 7, v150
	s_waitcnt lgkmcnt(0)
	v_lshlrev_b32_e32 v1, 7, v40
	v_and_or_b32 v1, v1, s68, v150
	global_load_dwordx4 v[32:35], v0, s[26:27]
	global_load_dwordx4 v[28:31], v1, s[26:27]
	v_bfe_u32 v0, v40, 16, 16
	v_lshl_or_b32 v0, v0, 7, v150
	v_lshlrev_b32_e32 v1, 7, v41
	v_and_or_b32 v1, v1, s68, v150
	global_load_dwordx4 v[24:27], v0, s[26:27]
	global_load_dwordx4 v[20:23], v1, s[26:27]
	v_bfe_u32 v0, v41, 16, 16
	v_lshl_or_b32 v0, v0, 7, v150
	v_lshlrev_b32_e32 v1, 7, v42
	v_and_or_b32 v1, v1, s68, v150
	global_load_dwordx4 v[16:19], v0, s[26:27]
	global_load_dwordx4 v[12:15], v1, s[26:27]
	v_bfe_u32 v0, v42, 16, 16
	v_lshl_or_b32 v0, v0, 7, v150
	v_lshlrev_b32_e32 v1, 7, v43
	v_and_or_b32 v1, v1, s68, v150
	global_load_dwordx4 v[8:11], v0, s[26:27]
	global_load_dwordx4 v[4:7], v1, s[26:27]
	v_bfe_u32 v0, v43, 16, 16
	v_lshl_or_b32 v0, v0, 7, v150
	global_load_dwordx4 v[0:3], v0, s[26:27]
	s_nop 0
	global_load_dwordx4 v[64:67], v64, s[26:27]
	s_nop 0
	global_load_dwordx4 v[40:43], v[144:145], off
	ds_read_b128 v[140:143], v185 offset:256
	ds_read_b128 v[136:139], v185 offset:272
	s_mov_b32 s76, 0
	s_branch .LBB0_1379
